# stack2: + first K-loop iteration peeled with inline-0 accumulator inputs (no accumulator zeroing v_movs) in in-proj/up-proj/down-proj, + L1 invalidate of the per-XCD seam issued right after the arriva
# speedup vs baseline: 1.0256x; 1.0137x over previous
; #define PG8_STAGE(bufoff, gbase, voff) do { _Pragma("unroll") for (int _i = 0; _i < 2; ++_i) \
;         __builtin_amdgcn_global_load_lds((const unsigned*)((const char*)(gbase) + (voff)[_i]), (PG8_LAS unsigned*)(lds + (bufoff) + ldsw + _i * 8192), 16, 0, 0); } while (0)
; #define PG8_LDA(dst, b, h) do { _Pragma("unroll") for (int m = 0; m < 4; ++m) _Pragma("unroll") for (int k = 0; k < 2; ++k) dst[m][k] = *(const PG8_LAS bf16x8*)(lds + PG8_SA(b, h) + aoff + m * 2048 + k * 1024); } while (0)
; #define PG8_LDB(dst, b, h) do { _Pragma("unroll") for (int n = 0; n < 2; ++n) _Pragma("unroll") for (int k = 0; k < 2; ++k) dst[n][k] = *(const PG8_LAS bf16x8*)(lds + PG8_SB(b, h) + boff + n * 2048 + k * 1024); } while (0)
; #define PG8_MMA(ai, bj, At, Bt) do { __builtin_amdgcn_s_setprio(1); _Pragma("unroll") for (int m = 0; m < 4; ++m) _Pragma("unroll") for (int n = 0; n < 2; ++n) _Pragma("unroll") for (int k = 0; k < 2; ++k) \
;         acc[ai][bj][m][n] = __builtin_amdgcn_mfma_f32_16x16x32_bf16(Bt[n][k], At[m][k], acc[ai][bj][m][n], 0, 0, 0); __builtin_amdgcn_s_setprio(0); } while (0)
; #define PG8_WAIT_V(n) asm volatile("s_waitcnt vmcnt(" #n ")" ::: "memory")
; #define PG8_WAIT_L(n) asm volatile("s_waitcnt lgkmcnt(" #n ")" ::: "memory")
; template <class Epi, class Sched, bool ALIGN_EPI = false, bool SP2 = false>
; __device__ __forceinline__ void gemm_phase(PG8_LAS unsigned char* lds, const Gemm g, const Sched& S, const Epi& E, int tid_in) {
;     ...
;             const bool last = (t == nt - 2);
;             const char* a1 = cA + (size_t)(t + 1) * kstep;
;             const char* a2 = last ? nA : cA + (size_t)(t + 2) * kstep; const char* b2 = last ? nB : cB + (size_t)(t + 2) * kstep;
;             const char* a3 = a2 + kstep; const char* b3 = b2 + kstep;
;             if (last && has_next) S.a_ready(nxt);
;             if constexpr (SP2) {
;             PG8_LDB(B0, 0, 0); PG8_LDB(B1, 0, 1); PG8_SCHED; PG8_LDA(At, 0, 0); PG8_STAGE(PG8_SA(1, 1), a1 + hstep, voffA);
;             PG8_WAIT_V(8); PG8_WAIT_L(0); PG8_BAR; PG8_MMA(0, 0, At, B0); PG8_MMA(0, 1, At, B1); PG8_BAR; PG8_SCHED;
;             PG8_LDA(At, 0, 1); PG8_STAGE(PG8_SB(0, 0), b2, voffB); PG8_STAGE(PG8_SB(0, 1), b2 + hstep, voffB); PG8_STAGE(PG8_SA(0, 0), a2, voffA);
;             PG8_WAIT_V(8); PG8_WAIT_L(0); PG8_BAR; PG8_MMA(1, 0, At, B0); PG8_MMA(1, 1, At, B1); PG8_BAR; PG8_SCHED;
.LBB0_74:
	s_add_u32 s30, s24, 0x100
	s_addc_u32 s31, s25, 0
	s_mov_b32 s44, -2
	s_waitcnt vmcnt(0)
	s_add_u32 s24, s22, 0x100
	s_addc_u32 s25, s23, 0
	s_add_i32 s45, 0, 0x10000
	s_cmp_eq_u32 s44, 40
	s_cselect_b32 s29, s61, s25
	s_cselect_b32 s28, s60, s24
	s_cselect_b32 s27, s21, s31
	s_cselect_b32 s26, s20, s30
	s_add_i32 s48, 0, 0x14000
	v_add_u32_e32 v152, s45, v159
	v_add_u32_e32 v156, s48, v159
	ds_read_b128 v[130:133], v152
	ds_read_b128 v[134:137], v152 offset:1024
	ds_read_b128 v[148:151], v152 offset:2048
	ds_read_b128 v[152:155], v152 offset:3072
	ds_read_b128 v[180:183], v156
	ds_read_b128 v[184:187], v156 offset:1024
	ds_read_b128 v[188:191], v156 offset:2048
	ds_read_b128 v[192:195], v156 offset:3072
	v_lshl_add_u64 v[156:157], s[22:23], 0, v[144:145]
	s_add_i32 m0, s62, 0xc000
	ds_read_b128 v[196:199], v178
	ds_read_b128 v[200:203], v178 offset:1024
	ds_read_b128 v[204:207], v178 offset:2048
	ds_read_b128 v[208:211], v178 offset:3072
	ds_read_b128 v[212:215], v178 offset:4096
	ds_read_b128 v[216:219], v178 offset:5120
	ds_read_b128 v[220:223], v178 offset:6144
	ds_read_b128 v[242:245], v178 offset:7168
	global_load_lds_dwordx4 v[156:157], off
	v_lshl_add_u64 v[156:157], s[22:23], 0, v[146:147]
	s_add_i32 m0, s62, 0xe000
	s_nop 0
	global_load_lds_dwordx4 v[156:157], off
	s_waitcnt vmcnt(8)
	s_waitcnt lgkmcnt(0)
	s_barrier
	s_setprio 1
	s_waitcnt lgkmcnt(0)
	v_mfma_f32_16x16x32_bf16 v[126:129], v[130:133], v[196:199], 0
	v_mfma_f32_16x16x32_bf16 v[122:125], v[148:151], v[196:199], 0
	v_mfma_f32_16x16x32_bf16 v[110:113], v[130:133], v[204:207], 0
	v_mfma_f32_16x16x32_bf16 v[106:109], v[148:151], v[204:207], 0
	v_mfma_f32_16x16x32_bf16 v[94:97], v[130:133], v[212:215], 0
	v_mfma_f32_16x16x32_bf16 v[90:93], v[148:151], v[212:215], 0
	v_mfma_f32_16x16x32_bf16 v[78:81], v[130:133], v[220:223], 0
	v_mfma_f32_16x16x32_bf16 v[74:77], v[148:151], v[220:223], 0
	v_mfma_f32_16x16x32_bf16 v[126:129], v[134:137], v[200:203], v[126:129]
	v_mfma_f32_16x16x32_bf16 v[122:125], v[152:155], v[200:203], v[122:125]
	v_mfma_f32_16x16x32_bf16 v[110:113], v[134:137], v[208:211], v[110:113]
	v_mfma_f32_16x16x32_bf16 v[106:109], v[152:155], v[208:211], v[106:109]
	v_mfma_f32_16x16x32_bf16 v[94:97], v[134:137], v[216:219], v[94:97]
	v_mfma_f32_16x16x32_bf16 v[90:93], v[152:155], v[216:219], v[90:93]
	v_mfma_f32_16x16x32_bf16 v[78:81], v[134:137], v[242:245], v[78:81]
	v_mfma_f32_16x16x32_bf16 v[74:77], v[152:155], v[242:245], v[74:77]
	v_mfma_f32_16x16x32_bf16 v[118:121], v[180:183], v[196:199], 0
	v_mfma_f32_16x16x32_bf16 v[114:117], v[188:191], v[196:199], 0
	v_mfma_f32_16x16x32_bf16 v[102:105], v[180:183], v[204:207], 0
	v_mfma_f32_16x16x32_bf16 v[98:101], v[188:191], v[204:207], 0
	v_mfma_f32_16x16x32_bf16 v[86:89], v[180:183], v[212:215], 0
	v_mfma_f32_16x16x32_bf16 v[82:85], v[188:191], v[212:215], 0
	v_mfma_f32_16x16x32_bf16 v[70:73], v[180:183], v[220:223], 0
	v_mfma_f32_16x16x32_bf16 v[66:69], v[188:191], v[220:223], 0
	v_mfma_f32_16x16x32_bf16 v[118:121], v[184:187], v[200:203], v[118:121]
	v_mfma_f32_16x16x32_bf16 v[114:117], v[192:195], v[200:203], v[114:117]
	v_mfma_f32_16x16x32_bf16 v[102:105], v[184:187], v[208:211], v[102:105]
	v_mfma_f32_16x16x32_bf16 v[98:101], v[192:195], v[208:211], v[98:101]
	v_mfma_f32_16x16x32_bf16 v[86:89], v[184:187], v[216:219], v[86:89]
	v_mfma_f32_16x16x32_bf16 v[82:85], v[192:195], v[216:219], v[82:85]
	v_mfma_f32_16x16x32_bf16 v[70:73], v[184:187], v[242:245], v[70:73]
	v_mfma_f32_16x16x32_bf16 v[66:69], v[192:195], v[242:245], v[66:69]
	s_setprio 0
	s_barrier
	s_add_i32 s22, s45, s37
	v_lshl_add_u64 v[156:157], s[26:27], 0, v[64:65]
	s_mov_b32 m0, s22
	ds_read_b128 v[196:199], v178 offset:16384
	ds_read_b128 v[200:203], v178 offset:17408
	ds_read_b128 v[204:207], v178 offset:18432
	ds_read_b128 v[208:211], v178 offset:19456
	ds_read_b128 v[212:215], v178 offset:20480
	ds_read_b128 v[216:219], v178 offset:21504
	ds_read_b128 v[220:223], v178 offset:22528
	ds_read_b128 v[242:245], v178 offset:23552
	global_load_lds_dwordx4 v[156:157], off
	s_add_i32 m0, s22, 0x2000
	s_add_u32 s22, s26, 0xb0000
	v_lshl_add_u64 v[172:173], s[26:27], 0, v[142:143]
	s_addc_u32 s23, s27, 0
	s_add_i32 s45, s48, s37
	global_load_lds_dwordx4 v[172:173], off
	v_lshl_add_u64 v[224:225], s[22:23], 0, v[64:65]
	s_mov_b32 m0, s45
	v_lshl_add_u64 v[232:233], s[28:29], 0, v[140:141]
	global_load_lds_dwordx4 v[224:225], off
	v_lshl_add_u64 v[224:225], s[22:23], 0, v[142:143]
	s_add_i32 m0, s45, 0x2000
	s_nop 0
	global_load_lds_dwordx4 v[224:225], off
	v_lshl_add_u64 v[224:225], s[28:29], 0, v[138:139]
	s_mov_b32 m0, s62
	s_nop 0
	global_load_lds_dwordx4 v[224:225], off
	s_mov_b32 m0, s63
	s_nop 0
	global_load_lds_dwordx4 v[232:233], off
	s_waitcnt vmcnt(8)
	s_waitcnt lgkmcnt(0)
	s_barrier
; #define PG8_STAGE(bufoff, gbase, voff) do { _Pragma("unroll") for (int _i = 0; _i < 2; ++_i) \
;         __builtin_amdgcn_global_load_lds((const unsigned*)((const char*)(gbase) + (voff)[_i]), (PG8_LAS unsigned*)(lds + (bufoff) + ldsw + _i * 8192), 16, 0, 0); } while (0)
; #define PG8_LDA(dst, b, h) do { _Pragma("unroll") for (int m = 0; m < 4; ++m) _Pragma("unroll") for (int k = 0; k < 2; ++k) dst[m][k] = *(const PG8_LAS bf16x8*)(lds + PG8_SA(b, h) + aoff + m * 2048 + k * 1024); } while (0)
; #define PG8_LDB(dst, b, h) do { _Pragma("unroll") for (int n = 0; n < 2; ++n) _Pragma("unroll") for (int k = 0; k < 2; ++k) dst[n][k] = *(const PG8_LAS bf16x8*)(lds + PG8_SB(b, h) + boff + n * 2048 + k * 1024); } while (0)
; #define PG8_MMA(ai, bj, At, Bt) do { __builtin_amdgcn_s_setprio(1); _Pragma("unroll") for (int m = 0; m < 4; ++m) _Pragma("unroll") for (int n = 0; n < 2; ++n) _Pragma("unroll") for (int k = 0; k < 2; ++k) \
;         acc[ai][bj][m][n] = __builtin_amdgcn_mfma_f32_16x16x32_bf16(Bt[n][k], At[m][k], acc[ai][bj][m][n], 0, 0, 0); __builtin_amdgcn_s_setprio(0); } while (0)
; #define PG8_WAIT_V(n) asm volatile("s_waitcnt vmcnt(" #n ")" ::: "memory")
; #define PG8_WAIT_L(n) asm volatile("s_waitcnt lgkmcnt(" #n ")" ::: "memory")
; #define PG8_BAR __builtin_amdgcn_s_barrier()
; #define PG8_SCHED __builtin_amdgcn_sched_barrier(0)
; template <class Epi, class Sched, bool ALIGN_EPI = false, bool SP2 = false>
; __device__ __forceinline__ void gemm_phase(PG8_LAS unsigned char* lds, const Gemm g, const Sched& S, const Epi& E, int tid_in) {
;     ...
;             PG8_WAIT_V(8); PG8_WAIT_L(0); PG8_BAR; PG8_MMA(1, 0, At, B0); PG8_MMA(1, 1, At, B1); PG8_BAR; PG8_SCHED;
;             PG8_LDB(B0, 1, 0); PG8_LDB(B1, 1, 1); PG8_SCHED; PG8_LDA(At, 1, 0); PG8_STAGE(PG8_SA(0, 1), a2 + hstep, voffA);
;             PG8_WAIT_V(8); PG8_WAIT_L(0); PG8_BAR; PG8_MMA(0, 0, At, B0); PG8_MMA(0, 1, At, B1); PG8_BAR; PG8_SCHED;
	s_setprio 1
	s_waitcnt lgkmcnt(0)
	v_mfma_f32_16x16x32_bf16 v[60:63], v[130:133], v[196:199], 0
	v_mfma_f32_16x16x32_bf16 v[56:59], v[148:151], v[196:199], 0
	v_mfma_f32_16x16x32_bf16 v[44:47], v[130:133], v[204:207], 0
	v_mfma_f32_16x16x32_bf16 v[40:43], v[148:151], v[204:207], 0
	v_mfma_f32_16x16x32_bf16 v[28:31], v[130:133], v[212:215], 0
	v_mfma_f32_16x16x32_bf16 v[24:27], v[148:151], v[212:215], 0
	v_mfma_f32_16x16x32_bf16 v[12:15], v[130:133], v[220:223], 0
	v_mfma_f32_16x16x32_bf16 v[8:11], v[148:151], v[220:223], 0
	v_mfma_f32_16x16x32_bf16 v[60:63], v[134:137], v[200:203], v[60:63]
	v_mfma_f32_16x16x32_bf16 v[56:59], v[152:155], v[200:203], v[56:59]
	v_mfma_f32_16x16x32_bf16 v[44:47], v[134:137], v[208:211], v[44:47]
	v_mfma_f32_16x16x32_bf16 v[40:43], v[152:155], v[208:211], v[40:43]
	v_mfma_f32_16x16x32_bf16 v[28:31], v[134:137], v[216:219], v[28:31]
	v_mfma_f32_16x16x32_bf16 v[24:27], v[152:155], v[216:219], v[24:27]
	v_mfma_f32_16x16x32_bf16 v[12:15], v[134:137], v[242:245], v[12:15]
	v_mfma_f32_16x16x32_bf16 v[8:11], v[152:155], v[242:245], v[8:11]
	v_mfma_f32_16x16x32_bf16 v[52:55], v[180:183], v[196:199], 0
	v_mfma_f32_16x16x32_bf16 v[48:51], v[188:191], v[196:199], 0
	v_mfma_f32_16x16x32_bf16 v[36:39], v[180:183], v[204:207], 0
	v_mfma_f32_16x16x32_bf16 v[32:35], v[188:191], v[204:207], 0
	v_mfma_f32_16x16x32_bf16 v[20:23], v[180:183], v[212:215], 0
	v_mfma_f32_16x16x32_bf16 v[16:19], v[188:191], v[212:215], 0
	v_mfma_f32_16x16x32_bf16 v[4:7], v[180:183], v[220:223], 0
	v_mfma_f32_16x16x32_bf16 v[0:3], v[188:191], v[220:223], 0
	v_mfma_f32_16x16x32_bf16 v[52:55], v[184:187], v[200:203], v[52:55]
	v_mfma_f32_16x16x32_bf16 v[48:51], v[192:195], v[200:203], v[48:51]
	v_mfma_f32_16x16x32_bf16 v[36:39], v[184:187], v[208:211], v[36:39]
	v_mfma_f32_16x16x32_bf16 v[32:35], v[192:195], v[208:211], v[32:35]
	v_mfma_f32_16x16x32_bf16 v[20:23], v[184:187], v[216:219], v[20:23]
	v_mfma_f32_16x16x32_bf16 v[16:19], v[192:195], v[216:219], v[16:19]
	v_mfma_f32_16x16x32_bf16 v[4:7], v[184:187], v[242:245], v[4:7]
	v_mfma_f32_16x16x32_bf16 v[0:3], v[192:195], v[242:245], v[0:3]
	s_setprio 0
	s_barrier
	s_add_i32 s45, 0, 0x18000
	s_add_i32 s48, 0, 0x1c000
	v_add_u32_e32 v152, s45, v159
	v_add_u32_e32 v179, s48, v159
	ds_read_b128 v[130:133], v152
	ds_read_b128 v[134:137], v152 offset:1024
	ds_read_b128 v[148:151], v152 offset:2048
	ds_read_b128 v[152:155], v152 offset:3072
	ds_read_b128 v[180:183], v179
	ds_read_b128 v[184:187], v179 offset:1024
	ds_read_b128 v[188:191], v179 offset:2048
	ds_read_b128 v[192:195], v179 offset:3072
	s_add_u32 s22, s28, 0xb0000
	s_addc_u32 s23, s29, 0
	s_mov_b32 m0, s66
	v_lshl_add_u64 v[238:239], s[22:23], 0, v[138:139]
	ds_read_b128 v[196:199], v178 offset:32768
	ds_read_b128 v[200:203], v178 offset:33792
	ds_read_b128 v[204:207], v178 offset:34816
	ds_read_b128 v[208:211], v178 offset:35840
	ds_read_b128 v[212:215], v178 offset:36864
	ds_read_b128 v[216:219], v178 offset:37888
	ds_read_b128 v[220:223], v178 offset:38912
	ds_read_b128 v[242:245], v178 offset:39936
	global_load_lds_dwordx4 v[238:239], off
	v_lshl_add_u64 v[238:239], s[22:23], 0, v[140:141]
	s_mov_b32 m0, s67
	s_nop 0
	global_load_lds_dwordx4 v[238:239], off
	s_waitcnt vmcnt(8)
	s_waitcnt lgkmcnt(0)
	s_barrier
	s_setprio 1
	s_waitcnt lgkmcnt(0)
	v_mfma_f32_16x16x32_bf16 v[126:129], v[130:133], v[196:199], v[126:129]
	v_mfma_f32_16x16x32_bf16 v[122:125], v[148:151], v[196:199], v[122:125]
	v_mfma_f32_16x16x32_bf16 v[110:113], v[130:133], v[204:207], v[110:113]
	v_mfma_f32_16x16x32_bf16 v[106:109], v[148:151], v[204:207], v[106:109]
	v_mfma_f32_16x16x32_bf16 v[94:97], v[130:133], v[212:215], v[94:97]
	v_mfma_f32_16x16x32_bf16 v[90:93], v[148:151], v[212:215], v[90:93]
	v_mfma_f32_16x16x32_bf16 v[78:81], v[130:133], v[220:223], v[78:81]
	v_mfma_f32_16x16x32_bf16 v[74:77], v[148:151], v[220:223], v[74:77]
	v_mfma_f32_16x16x32_bf16 v[126:129], v[134:137], v[200:203], v[126:129]
	v_mfma_f32_16x16x32_bf16 v[122:125], v[152:155], v[200:203], v[122:125]
	v_mfma_f32_16x16x32_bf16 v[110:113], v[134:137], v[208:211], v[110:113]
	v_mfma_f32_16x16x32_bf16 v[106:109], v[152:155], v[208:211], v[106:109]
	v_mfma_f32_16x16x32_bf16 v[94:97], v[134:137], v[216:219], v[94:97]
	v_mfma_f32_16x16x32_bf16 v[90:93], v[152:155], v[216:219], v[90:93]
	v_mfma_f32_16x16x32_bf16 v[78:81], v[134:137], v[242:245], v[78:81]
	v_mfma_f32_16x16x32_bf16 v[74:77], v[152:155], v[242:245], v[74:77]
	v_mfma_f32_16x16x32_bf16 v[118:121], v[180:183], v[196:199], v[118:121]
	v_mfma_f32_16x16x32_bf16 v[114:117], v[188:191], v[196:199], v[114:117]
	v_mfma_f32_16x16x32_bf16 v[102:105], v[180:183], v[204:207], v[102:105]
	v_mfma_f32_16x16x32_bf16 v[98:101], v[188:191], v[204:207], v[98:101]
	v_mfma_f32_16x16x32_bf16 v[86:89], v[180:183], v[212:215], v[86:89]
	v_mfma_f32_16x16x32_bf16 v[82:85], v[188:191], v[212:215], v[82:85]
	v_mfma_f32_16x16x32_bf16 v[70:73], v[180:183], v[220:223], v[70:73]
	v_mfma_f32_16x16x32_bf16 v[66:69], v[188:191], v[220:223], v[66:69]
	v_mfma_f32_16x16x32_bf16 v[118:121], v[184:187], v[200:203], v[118:121]
	v_mfma_f32_16x16x32_bf16 v[114:117], v[192:195], v[200:203], v[114:117]
	v_mfma_f32_16x16x32_bf16 v[102:105], v[184:187], v[208:211], v[102:105]
	v_mfma_f32_16x16x32_bf16 v[98:101], v[192:195], v[208:211], v[98:101]
	v_mfma_f32_16x16x32_bf16 v[86:89], v[184:187], v[216:219], v[86:89]
	v_mfma_f32_16x16x32_bf16 v[82:85], v[192:195], v[216:219], v[82:85]
	v_mfma_f32_16x16x32_bf16 v[70:73], v[184:187], v[242:245], v[70:73]
	v_mfma_f32_16x16x32_bf16 v[66:69], v[192:195], v[242:245], v[66:69]
	s_setprio 0
	s_barrier
; #define PG8_STAGE(bufoff, gbase, voff) do { _Pragma("unroll") for (int _i = 0; _i < 2; ++_i) \
;         __builtin_amdgcn_global_load_lds((const unsigned*)((const char*)(gbase) + (voff)[_i]), (PG8_LAS unsigned*)(lds + (bufoff) + ldsw + _i * 8192), 16, 0, 0); } while (0)
; #define PG8_LDA(dst, b, h) do { _Pragma("unroll") for (int m = 0; m < 4; ++m) _Pragma("unroll") for (int k = 0; k < 2; ++k) dst[m][k] = *(const PG8_LAS bf16x8*)(lds + PG8_SA(b, h) + aoff + m * 2048 + k * 1024); } while (0)
; #define PG8_MMA(ai, bj, At, Bt) do { __builtin_amdgcn_s_setprio(1); _Pragma("unroll") for (int m = 0; m < 4; ++m) _Pragma("unroll") for (int n = 0; n < 2; ++n) _Pragma("unroll") for (int k = 0; k < 2; ++k) \
;         acc[ai][bj][m][n] = __builtin_amdgcn_mfma_f32_16x16x32_bf16(Bt[n][k], At[m][k], acc[ai][bj][m][n], 0, 0, 0); __builtin_amdgcn_s_setprio(0); } while (0)
; #define PG8_WAIT_V(n) asm volatile("s_waitcnt vmcnt(" #n ")" ::: "memory")
; #define PG8_WAIT_L(n) asm volatile("s_waitcnt lgkmcnt(" #n ")" ::: "memory")
; #define PG8_BAR __builtin_amdgcn_s_barrier()
; #define PG8_SCHED __builtin_amdgcn_sched_barrier(0)
; template <class Epi, class Sched, bool ALIGN_EPI = false, bool SP2 = false>
; __device__ __forceinline__ void gemm_phase(PG8_LAS unsigned char* lds, const Gemm g, const Sched& S, const Epi& E, int tid_in) {
;     ...
;             PG8_LDA(At, 1, 1); PG8_STAGE(PG8_SB(1, 0), b3, voffB); PG8_STAGE(PG8_SB(1, 1), b3 + hstep, voffB); PG8_STAGE(PG8_SA(1, 0), a3, voffA);
;             PG8_WAIT_V(8); PG8_WAIT_L(0); PG8_BAR; PG8_MMA(1, 0, At, B0); PG8_MMA(1, 1, At, B1); PG8_BAR; PG8_SCHED;
	s_add_i32 s22, s45, s37
	v_lshl_add_u64 v[156:157], v[156:157], 0, s[92:93]
	s_mov_b32 m0, s22
	ds_read_b128 v[196:199], v178 offset:49152
	ds_read_b128 v[200:203], v178 offset:50176
	ds_read_b128 v[204:207], v178 offset:51200
	ds_read_b128 v[208:211], v178 offset:52224
	ds_read_b128 v[212:215], v178 offset:53248
	ds_read_b128 v[216:219], v178 offset:54272
	ds_read_b128 v[220:223], v178 offset:55296
	ds_read_b128 v[242:245], v178 offset:56320
	global_load_lds_dwordx4 v[156:157], off
	s_add_i32 m0, s22, 0x2000
	s_add_u32 s22, s26, 0xb0080
	v_lshl_add_u64 v[156:157], v[172:173], 0, s[92:93]
	s_addc_u32 s23, s27, 0
	s_add_i32 s26, s48, s37
	global_load_lds_dwordx4 v[156:157], off
	v_lshl_add_u64 v[156:157], s[22:23], 0, v[64:65]
	s_mov_b32 m0, s26
	s_nop 0
	global_load_lds_dwordx4 v[156:157], off
	v_lshl_add_u64 v[156:157], s[22:23], 0, v[142:143]
	s_add_i32 m0, s26, 0x2000
	s_nop 0
	global_load_lds_dwordx4 v[156:157], off
	v_lshl_add_u64 v[156:157], v[224:225], 0, s[92:93]
	s_mov_b32 m0, s69
	s_nop 0
	global_load_lds_dwordx4 v[156:157], off
	v_lshl_add_u64 v[156:157], v[232:233], 0, s[92:93]
	s_mov_b32 m0, s74
	s_nop 0
	global_load_lds_dwordx4 v[156:157], off
	s_waitcnt vmcnt(8)
	s_waitcnt lgkmcnt(0)
	s_barrier
	s_setprio 1
	s_waitcnt lgkmcnt(0)
	v_mfma_f32_16x16x32_bf16 v[60:63], v[130:133], v[196:199], v[60:63]
	v_mfma_f32_16x16x32_bf16 v[56:59], v[148:151], v[196:199], v[56:59]
	v_mfma_f32_16x16x32_bf16 v[44:47], v[130:133], v[204:207], v[44:47]
	v_mfma_f32_16x16x32_bf16 v[40:43], v[148:151], v[204:207], v[40:43]
	v_mfma_f32_16x16x32_bf16 v[28:31], v[130:133], v[212:215], v[28:31]
	v_mfma_f32_16x16x32_bf16 v[24:27], v[148:151], v[212:215], v[24:27]
	v_mfma_f32_16x16x32_bf16 v[12:15], v[130:133], v[220:223], v[12:15]
	v_mfma_f32_16x16x32_bf16 v[8:11], v[148:151], v[220:223], v[8:11]
	v_mfma_f32_16x16x32_bf16 v[60:63], v[134:137], v[200:203], v[60:63]
	v_mfma_f32_16x16x32_bf16 v[56:59], v[152:155], v[200:203], v[56:59]
	v_mfma_f32_16x16x32_bf16 v[44:47], v[134:137], v[208:211], v[44:47]
	v_mfma_f32_16x16x32_bf16 v[40:43], v[152:155], v[208:211], v[40:43]
	v_mfma_f32_16x16x32_bf16 v[28:31], v[134:137], v[216:219], v[28:31]
	v_mfma_f32_16x16x32_bf16 v[24:27], v[152:155], v[216:219], v[24:27]
	v_mfma_f32_16x16x32_bf16 v[12:15], v[134:137], v[242:245], v[12:15]
	v_mfma_f32_16x16x32_bf16 v[8:11], v[152:155], v[242:245], v[8:11]
	v_mfma_f32_16x16x32_bf16 v[52:55], v[180:183], v[196:199], v[52:55]
	v_mfma_f32_16x16x32_bf16 v[48:51], v[188:191], v[196:199], v[48:51]
	v_mfma_f32_16x16x32_bf16 v[36:39], v[180:183], v[204:207], v[36:39]
	v_mfma_f32_16x16x32_bf16 v[32:35], v[188:191], v[204:207], v[32:35]
	v_mfma_f32_16x16x32_bf16 v[20:23], v[180:183], v[212:215], v[20:23]
	v_mfma_f32_16x16x32_bf16 v[16:19], v[188:191], v[212:215], v[16:19]
	v_mfma_f32_16x16x32_bf16 v[4:7], v[180:183], v[220:223], v[4:7]
	v_mfma_f32_16x16x32_bf16 v[0:3], v[188:191], v[220:223], v[0:3]
	v_mfma_f32_16x16x32_bf16 v[52:55], v[184:187], v[200:203], v[52:55]
	v_mfma_f32_16x16x32_bf16 v[48:51], v[192:195], v[200:203], v[48:51]
	v_mfma_f32_16x16x32_bf16 v[36:39], v[184:187], v[208:211], v[36:39]
	v_mfma_f32_16x16x32_bf16 v[32:35], v[192:195], v[208:211], v[32:35]
	v_mfma_f32_16x16x32_bf16 v[20:23], v[184:187], v[216:219], v[20:23]
	v_mfma_f32_16x16x32_bf16 v[16:19], v[192:195], v[216:219], v[16:19]
	v_mfma_f32_16x16x32_bf16 v[4:7], v[184:187], v[242:245], v[4:7]
	v_mfma_f32_16x16x32_bf16 v[0:3], v[192:195], v[242:245], v[0:3]
	s_setprio 0
	s_barrier
	s_add_i32 s44, s44, 2
	s_add_u32 s30, s30, 0x100
	s_addc_u32 s31, s31, 0
	s_cmp_gt_u32 s44, 41
	s_mov_b64 s[22:23], s[24:25]
	s_cbranch_scc0 .LBB0_75
	s_branch .Lpeel_exit_2

; #define PG8_BAR __builtin_amdgcn_s_barrier()
; template <class Epi, class Sched, bool ALIGN_EPI = false, bool SP2 = false>
; __device__ __forceinline__ void gemm_phase(PG8_LAS unsigned char* lds, const Gemm g, const Sched& S, const Epi& E, int tid_in) {
;     ...
;         if constexpr (ALIGN_EPI) { if (wr == 0) PG8_BAR; }
.Lpeel_exit_2:
	s_and_b64 vcc, exec, s[46:47]
	s_cbranch_vccz .LBB0_78
	s_barrier

; #define PG8_STAGE(bufoff, gbase, voff) do { _Pragma("unroll") for (int _i = 0; _i < 2; ++_i) \
;         __builtin_amdgcn_global_load_lds((const unsigned*)((const char*)(gbase) + (voff)[_i]), (PG8_LAS unsigned*)(lds + (bufoff) + ldsw + _i * 8192), 16, 0, 0); } while (0)
; #define PG8_LDA(dst, b, h) do { _Pragma("unroll") for (int m = 0; m < 4; ++m) _Pragma("unroll") for (int k = 0; k < 2; ++k) dst[m][k] = *(const PG8_LAS bf16x8*)(lds + PG8_SA(b, h) + aoff + m * 2048 + k * 1024); } while (0)
; #define PG8_LDB(dst, b, h) do { _Pragma("unroll") for (int n = 0; n < 2; ++n) _Pragma("unroll") for (int k = 0; k < 2; ++k) dst[n][k] = *(const PG8_LAS bf16x8*)(lds + PG8_SB(b, h) + boff + n * 2048 + k * 1024); } while (0)
; #define PG8_MMA(ai, bj, At, Bt) do { __builtin_amdgcn_s_setprio(1); _Pragma("unroll") for (int m = 0; m < 4; ++m) _Pragma("unroll") for (int n = 0; n < 2; ++n) _Pragma("unroll") for (int k = 0; k < 2; ++k) \
;         acc[ai][bj][m][n] = __builtin_amdgcn_mfma_f32_16x16x32_bf16(Bt[n][k], At[m][k], acc[ai][bj][m][n], 0, 0, 0); __builtin_amdgcn_s_setprio(0); } while (0)
; #define PG8_WAIT_V(n) asm volatile("s_waitcnt vmcnt(" #n ")" ::: "memory")
; #define PG8_WAIT_L(n) asm volatile("s_waitcnt lgkmcnt(" #n ")" ::: "memory")
; template <class Epi, class Sched, bool ALIGN_EPI = false, bool SP2 = false>
; __device__ __forceinline__ void gemm_phase(PG8_LAS unsigned char* lds, const Gemm g, const Sched& S, const Epi& E, int tid_in) {
;     ...
;             const bool last = (t == nt - 2);
;             const char* a1 = cA + (size_t)(t + 1) * kstep;
;             const char* a2 = last ? nA : cA + (size_t)(t + 2) * kstep; const char* b2 = last ? nB : cB + (size_t)(t + 2) * kstep;
;             const char* a3 = a2 + kstep; const char* b3 = b2 + kstep;
;             if (last && has_next) S.a_ready(nxt);
;             if constexpr (SP2) {
;             PG8_LDB(B0, 0, 0); PG8_LDB(B1, 0, 1); PG8_SCHED; PG8_LDA(At, 0, 0); PG8_STAGE(PG8_SA(1, 1), a1 + hstep, voffA);
;             PG8_WAIT_V(8); PG8_WAIT_L(0); PG8_BAR; PG8_MMA(0, 0, At, B0); PG8_MMA(0, 1, At, B1); PG8_BAR; PG8_SCHED;
;             PG8_LDA(At, 0, 1); PG8_STAGE(PG8_SB(0, 0), b2, voffB); PG8_STAGE(PG8_SB(0, 1), b2 + hstep, voffB); PG8_STAGE(PG8_SA(0, 0), a2, voffA);
;             PG8_WAIT_V(8); PG8_WAIT_L(0); PG8_BAR; PG8_MMA(1, 0, At, B0); PG8_MMA(1, 1, At, B1); PG8_BAR; PG8_SCHED;
.LBB0_241:
	s_ashr_i32 s51, s50, 31
	s_lshl_b64 s[30:31], s[50:51], 19
	s_add_u32 s56, s37, s30
	s_addc_u32 s57, s62, s31
	s_and_b64 s[30:31], s[40:41], exec
	s_cselect_b32 s23, s57, s27
	s_cselect_b32 s25, s56, s26
	s_ashr_i32 s49, s48, 31
	s_lshl_b64 s[30:31], s[48:49], 19
	s_add_u32 s60, s63, s30
	s_addc_u32 s61, s66, s31
	s_and_b64 s[30:31], s[40:41], exec
	s_cselect_b32 s34, s61, s29
	s_cselect_b32 s35, s60, s28
	s_add_u32 s26, s26, 0x40080
	s_addc_u32 s27, s27, 0
	s_add_u32 s42, s28, 0x100
	s_addc_u32 s43, s29, 0
	s_mov_b32 s44, -2
	s_waitcnt vmcnt(0)
	s_add_u32 s28, s26, 0xfffc0080
	s_addc_u32 s29, s27, -1
	s_add_i32 s45, 0, 0x10000
	s_cmp_eq_u32 s44, 12
	s_cselect_b32 s31, s23, s29
	s_cselect_b32 s30, s25, s28
	v_add_u32_e32 v64, s45, v171
	s_cselect_b32 s29, s34, s43
	s_cselect_b32 s28, s35, s42
	s_add_i32 s49, 0, 0x14000
	ds_read_b128 v[122:125], v64
	ds_read_b128 v[126:129], v64 offset:1024
	ds_read_b128 v[130:133], v64 offset:2048
	ds_read_b128 v[134:137], v64 offset:3072
	v_add_u32_e32 v64, s49, v171
	ds_read_b128 v[146:149], v64
	ds_read_b128 v[150:153], v64 offset:1024
	ds_read_b128 v[154:157], v64 offset:2048
	ds_read_b128 v[158:161], v64 offset:3072
	v_lshl_add_u64 v[172:173], s[26:27], 0, v[188:189]
	s_add_i32 m0, s67, 0xc000
	ds_read_b128 v[162:165], v216
	ds_read_b128 v[166:169], v216 offset:1024
	ds_read_b128 v[192:195], v216 offset:2048
	ds_read_b128 v[196:199], v216 offset:3072
	ds_read_b128 v[200:203], v216 offset:4096
	ds_read_b128 v[204:207], v216 offset:5120
	ds_read_b128 v[208:211], v216 offset:6144
	ds_read_b128 v[212:215], v216 offset:7168
	global_load_lds_dwordx4 v[172:173], off
	v_lshl_add_u64 v[172:173], s[26:27], 0, v[190:191]
	s_add_i32 m0, s67, 0xe000
	s_nop 0
	global_load_lds_dwordx4 v[172:173], off
	s_waitcnt vmcnt(8)
	s_waitcnt lgkmcnt(0)
	s_barrier
	s_setprio 1
	s_waitcnt lgkmcnt(0)
	v_mfma_f32_16x16x32_bf16 v[114:117], v[122:125], v[162:165], 0
	v_mfma_f32_16x16x32_bf16 v[106:109], v[130:133], v[162:165], 0
	v_mfma_f32_16x16x32_bf16 v[142:145], v[122:125], v[192:195], 0
	v_mfma_f32_16x16x32_bf16 v[44:47], v[130:133], v[192:195], 0
	v_mfma_f32_16x16x32_bf16 v[110:113], v[122:125], v[200:203], 0
	v_mfma_f32_16x16x32_bf16 v[36:39], v[130:133], v[200:203], 0
	v_mfma_f32_16x16x32_bf16 v[118:121], v[122:125], v[208:211], 0
	v_mfma_f32_16x16x32_bf16 v[52:55], v[130:133], v[208:211], 0
	v_mfma_f32_16x16x32_bf16 v[114:117], v[126:129], v[166:169], v[114:117]
	v_mfma_f32_16x16x32_bf16 v[106:109], v[134:137], v[166:169], v[106:109]
	v_mfma_f32_16x16x32_bf16 v[142:145], v[126:129], v[196:199], v[142:145]
	v_mfma_f32_16x16x32_bf16 v[44:47], v[134:137], v[196:199], v[44:47]
	v_mfma_f32_16x16x32_bf16 v[110:113], v[126:129], v[204:207], v[110:113]
	v_mfma_f32_16x16x32_bf16 v[36:39], v[134:137], v[204:207], v[36:39]
	v_mfma_f32_16x16x32_bf16 v[118:121], v[126:129], v[212:215], v[118:121]
	v_mfma_f32_16x16x32_bf16 v[52:55], v[134:137], v[212:215], v[52:55]
	v_mfma_f32_16x16x32_bf16 v[102:105], v[146:149], v[162:165], 0
	v_mfma_f32_16x16x32_bf16 v[78:81], v[154:157], v[162:165], 0
	v_mfma_f32_16x16x32_bf16 v[138:141], v[146:149], v[192:195], 0
	v_mfma_f32_16x16x32_bf16 v[40:43], v[154:157], v[192:195], 0
	v_mfma_f32_16x16x32_bf16 v[98:101], v[146:149], v[200:203], 0
	v_mfma_f32_16x16x32_bf16 v[32:35], v[154:157], v[200:203], 0
	v_mfma_f32_16x16x32_bf16 v[94:97], v[146:149], v[208:211], 0
	v_mfma_f32_16x16x32_bf16 v[48:51], v[154:157], v[208:211], 0
	v_mfma_f32_16x16x32_bf16 v[102:105], v[150:153], v[166:169], v[102:105]
	v_mfma_f32_16x16x32_bf16 v[78:81], v[158:161], v[166:169], v[78:81]
	v_mfma_f32_16x16x32_bf16 v[138:141], v[150:153], v[196:199], v[138:141]
	v_mfma_f32_16x16x32_bf16 v[40:43], v[158:161], v[196:199], v[40:43]
	v_mfma_f32_16x16x32_bf16 v[98:101], v[150:153], v[204:207], v[98:101]
	v_mfma_f32_16x16x32_bf16 v[32:35], v[158:161], v[204:207], v[32:35]
	v_mfma_f32_16x16x32_bf16 v[94:97], v[150:153], v[212:215], v[94:97]
	v_mfma_f32_16x16x32_bf16 v[48:51], v[158:161], v[212:215], v[48:51]
	s_setprio 0
	s_barrier
	s_add_i32 s45, s45, s9
	v_lshl_add_u64 v[172:173], s[28:29], 0, v[178:179]
	s_mov_b32 m0, s45
	ds_read_b128 v[162:165], v216 offset:16384
	ds_read_b128 v[166:169], v216 offset:17408
	ds_read_b128 v[192:195], v216 offset:18432
	ds_read_b128 v[196:199], v216 offset:19456
	ds_read_b128 v[200:203], v216 offset:20480
	ds_read_b128 v[204:207], v216 offset:21504
	ds_read_b128 v[208:211], v216 offset:22528
	ds_read_b128 v[212:215], v216 offset:23552
	global_load_lds_dwordx4 v[172:173], off
	s_add_i32 m0, s45, 0x2000
	s_add_u32 s46, s28, 0x40000
	v_lshl_add_u64 v[220:221], s[28:29], 0, v[182:183]
	s_addc_u32 s47, s29, 0
	s_add_i32 s45, s49, s9
	global_load_lds_dwordx4 v[220:221], off
	v_lshl_add_u64 v[222:223], s[46:47], 0, v[178:179]
	s_mov_b32 m0, s45
	v_lshl_add_u64 v[224:225], s[30:31], 0, v[180:181]
	global_load_lds_dwordx4 v[222:223], off
	v_lshl_add_u64 v[222:223], s[46:47], 0, v[182:183]
	s_add_i32 m0, s45, 0x2000
	s_nop 0
	global_load_lds_dwordx4 v[222:223], off
	v_lshl_add_u64 v[222:223], s[30:31], 0, v[176:177]
	s_mov_b32 m0, s67
	s_nop 0
	global_load_lds_dwordx4 v[222:223], off
	s_mov_b32 m0, s69
	s_nop 0
	global_load_lds_dwordx4 v[224:225], off
	s_waitcnt vmcnt(8)
	s_waitcnt lgkmcnt(0)
	s_barrier
; #define PG8_STAGE(bufoff, gbase, voff) do { _Pragma("unroll") for (int _i = 0; _i < 2; ++_i) \
;         __builtin_amdgcn_global_load_lds((const unsigned*)((const char*)(gbase) + (voff)[_i]), (PG8_LAS unsigned*)(lds + (bufoff) + ldsw + _i * 8192), 16, 0, 0); } while (0)
; #define PG8_LDA(dst, b, h) do { _Pragma("unroll") for (int m = 0; m < 4; ++m) _Pragma("unroll") for (int k = 0; k < 2; ++k) dst[m][k] = *(const PG8_LAS bf16x8*)(lds + PG8_SA(b, h) + aoff + m * 2048 + k * 1024); } while (0)
; #define PG8_LDB(dst, b, h) do { _Pragma("unroll") for (int n = 0; n < 2; ++n) _Pragma("unroll") for (int k = 0; k < 2; ++k) dst[n][k] = *(const PG8_LAS bf16x8*)(lds + PG8_SB(b, h) + boff + n * 2048 + k * 1024); } while (0)
; #define PG8_MMA(ai, bj, At, Bt) do { __builtin_amdgcn_s_setprio(1); _Pragma("unroll") for (int m = 0; m < 4; ++m) _Pragma("unroll") for (int n = 0; n < 2; ++n) _Pragma("unroll") for (int k = 0; k < 2; ++k) \
;         acc[ai][bj][m][n] = __builtin_amdgcn_mfma_f32_16x16x32_bf16(Bt[n][k], At[m][k], acc[ai][bj][m][n], 0, 0, 0); __builtin_amdgcn_s_setprio(0); } while (0)
; #define PG8_WAIT_V(n) asm volatile("s_waitcnt vmcnt(" #n ")" ::: "memory")
; #define PG8_WAIT_L(n) asm volatile("s_waitcnt lgkmcnt(" #n ")" ::: "memory")
; #define PG8_BAR __builtin_amdgcn_s_barrier()
; #define PG8_SCHED __builtin_amdgcn_sched_barrier(0)
; template <class Epi, class Sched, bool ALIGN_EPI = false, bool SP2 = false>
; __device__ __forceinline__ void gemm_phase(PG8_LAS unsigned char* lds, const Gemm g, const Sched& S, const Epi& E, int tid_in) {
;     ...
;             PG8_WAIT_V(8); PG8_WAIT_L(0); PG8_BAR; PG8_MMA(1, 0, At, B0); PG8_MMA(1, 1, At, B1); PG8_BAR; PG8_SCHED;
;             PG8_LDB(B0, 1, 0); PG8_LDB(B1, 1, 1); PG8_SCHED; PG8_LDA(At, 1, 0); PG8_STAGE(PG8_SA(0, 1), a2 + hstep, voffA);
;             PG8_WAIT_V(8); PG8_WAIT_L(0); PG8_BAR; PG8_MMA(0, 0, At, B0); PG8_MMA(0, 1, At, B1); PG8_BAR; PG8_SCHED;
	s_setprio 1
	s_waitcnt lgkmcnt(0)
	v_mfma_f32_16x16x32_bf16 v[82:85], v[122:125], v[162:165], 0
	v_mfma_f32_16x16x32_bf16 v[20:23], v[130:133], v[162:165], 0
	v_mfma_f32_16x16x32_bf16 v[70:73], v[122:125], v[192:195], 0
	v_mfma_f32_16x16x32_bf16 v[12:15], v[130:133], v[192:195], 0
	v_mfma_f32_16x16x32_bf16 v[60:63], v[122:125], v[200:203], 0
	v_mfma_f32_16x16x32_bf16 v[4:7], v[130:133], v[200:203], 0
	v_mfma_f32_16x16x32_bf16 v[90:93], v[122:125], v[208:211], 0
	v_mfma_f32_16x16x32_bf16 v[28:31], v[130:133], v[208:211], 0
	v_mfma_f32_16x16x32_bf16 v[82:85], v[126:129], v[166:169], v[82:85]
	v_mfma_f32_16x16x32_bf16 v[20:23], v[134:137], v[166:169], v[20:23]
	v_mfma_f32_16x16x32_bf16 v[70:73], v[126:129], v[196:199], v[70:73]
	v_mfma_f32_16x16x32_bf16 v[12:15], v[134:137], v[196:199], v[12:15]
	v_mfma_f32_16x16x32_bf16 v[60:63], v[126:129], v[204:207], v[60:63]
	v_mfma_f32_16x16x32_bf16 v[4:7], v[134:137], v[204:207], v[4:7]
	v_mfma_f32_16x16x32_bf16 v[90:93], v[126:129], v[212:215], v[90:93]
	v_mfma_f32_16x16x32_bf16 v[28:31], v[134:137], v[212:215], v[28:31]
	v_mfma_f32_16x16x32_bf16 v[74:77], v[146:149], v[162:165], 0
	v_mfma_f32_16x16x32_bf16 v[16:19], v[154:157], v[162:165], 0
	v_mfma_f32_16x16x32_bf16 v[66:69], v[146:149], v[192:195], 0
	v_mfma_f32_16x16x32_bf16 v[8:11], v[154:157], v[192:195], 0
	v_mfma_f32_16x16x32_bf16 v[56:59], v[146:149], v[200:203], 0
	v_mfma_f32_16x16x32_bf16 v[0:3], v[154:157], v[200:203], 0
	v_mfma_f32_16x16x32_bf16 v[86:89], v[146:149], v[208:211], 0
	v_mfma_f32_16x16x32_bf16 v[24:27], v[154:157], v[208:211], 0
	v_mfma_f32_16x16x32_bf16 v[74:77], v[150:153], v[166:169], v[74:77]
	v_mfma_f32_16x16x32_bf16 v[16:19], v[158:161], v[166:169], v[16:19]
	v_mfma_f32_16x16x32_bf16 v[66:69], v[150:153], v[196:199], v[66:69]
	v_mfma_f32_16x16x32_bf16 v[8:11], v[158:161], v[196:199], v[8:11]
	v_mfma_f32_16x16x32_bf16 v[56:59], v[150:153], v[204:207], v[56:59]
	v_mfma_f32_16x16x32_bf16 v[0:3], v[158:161], v[204:207], v[0:3]
	v_mfma_f32_16x16x32_bf16 v[86:89], v[150:153], v[212:215], v[86:89]
	v_mfma_f32_16x16x32_bf16 v[24:27], v[158:161], v[212:215], v[24:27]
	s_setprio 0
	s_barrier
	s_add_i32 s45, 0, 0x18000
	v_add_u32_e32 v64, s45, v171
	s_add_i32 s46, 0, 0x1c000
	ds_read_b128 v[122:125], v64
	ds_read_b128 v[126:129], v64 offset:1024
	ds_read_b128 v[130:133], v64 offset:2048
	ds_read_b128 v[134:137], v64 offset:3072
	v_add_u32_e32 v64, s46, v171
	ds_read_b128 v[146:149], v64
	ds_read_b128 v[150:153], v64 offset:1024
	ds_read_b128 v[154:157], v64 offset:2048
	ds_read_b128 v[158:161], v64 offset:3072
	s_add_u32 s30, s30, 0x40000
	s_addc_u32 s31, s31, 0
	s_mov_b32 m0, s79
	v_lshl_add_u64 v[232:233], s[30:31], 0, v[176:177]
	ds_read_b128 v[162:165], v216 offset:32768
	ds_read_b128 v[166:169], v216 offset:33792
	ds_read_b128 v[192:195], v216 offset:34816
	ds_read_b128 v[196:199], v216 offset:35840
	ds_read_b128 v[200:203], v216 offset:36864
	ds_read_b128 v[204:207], v216 offset:37888
	ds_read_b128 v[208:211], v216 offset:38912
	ds_read_b128 v[212:215], v216 offset:39936
	global_load_lds_dwordx4 v[232:233], off
	v_lshl_add_u64 v[232:233], s[30:31], 0, v[180:181]
	s_mov_b32 m0, s82
	s_nop 0
	global_load_lds_dwordx4 v[232:233], off
	s_waitcnt vmcnt(8)
	s_waitcnt lgkmcnt(0)
	s_barrier
	s_setprio 1
	s_waitcnt lgkmcnt(0)
	v_mfma_f32_16x16x32_bf16 v[114:117], v[122:125], v[162:165], v[114:117]
	v_mfma_f32_16x16x32_bf16 v[106:109], v[130:133], v[162:165], v[106:109]
	v_mfma_f32_16x16x32_bf16 v[142:145], v[122:125], v[192:195], v[142:145]
	v_mfma_f32_16x16x32_bf16 v[44:47], v[130:133], v[192:195], v[44:47]
	v_mfma_f32_16x16x32_bf16 v[110:113], v[122:125], v[200:203], v[110:113]
	v_mfma_f32_16x16x32_bf16 v[36:39], v[130:133], v[200:203], v[36:39]
	v_mfma_f32_16x16x32_bf16 v[118:121], v[122:125], v[208:211], v[118:121]
	v_mfma_f32_16x16x32_bf16 v[52:55], v[130:133], v[208:211], v[52:55]
	v_mfma_f32_16x16x32_bf16 v[114:117], v[126:129], v[166:169], v[114:117]
	v_mfma_f32_16x16x32_bf16 v[106:109], v[134:137], v[166:169], v[106:109]
	v_mfma_f32_16x16x32_bf16 v[142:145], v[126:129], v[196:199], v[142:145]
	v_mfma_f32_16x16x32_bf16 v[44:47], v[134:137], v[196:199], v[44:47]
	v_mfma_f32_16x16x32_bf16 v[110:113], v[126:129], v[204:207], v[110:113]
	v_mfma_f32_16x16x32_bf16 v[36:39], v[134:137], v[204:207], v[36:39]
	v_mfma_f32_16x16x32_bf16 v[118:121], v[126:129], v[212:215], v[118:121]
	v_mfma_f32_16x16x32_bf16 v[52:55], v[134:137], v[212:215], v[52:55]
	v_mfma_f32_16x16x32_bf16 v[102:105], v[146:149], v[162:165], v[102:105]
	v_mfma_f32_16x16x32_bf16 v[78:81], v[154:157], v[162:165], v[78:81]
	v_mfma_f32_16x16x32_bf16 v[138:141], v[146:149], v[192:195], v[138:141]
	v_mfma_f32_16x16x32_bf16 v[40:43], v[154:157], v[192:195], v[40:43]
	v_mfma_f32_16x16x32_bf16 v[98:101], v[146:149], v[200:203], v[98:101]
	v_mfma_f32_16x16x32_bf16 v[32:35], v[154:157], v[200:203], v[32:35]
	v_mfma_f32_16x16x32_bf16 v[94:97], v[146:149], v[208:211], v[94:97]
	v_mfma_f32_16x16x32_bf16 v[48:51], v[154:157], v[208:211], v[48:51]
	v_mfma_f32_16x16x32_bf16 v[102:105], v[150:153], v[166:169], v[102:105]
	v_mfma_f32_16x16x32_bf16 v[78:81], v[158:161], v[166:169], v[78:81]
	v_mfma_f32_16x16x32_bf16 v[138:141], v[150:153], v[196:199], v[138:141]
	v_mfma_f32_16x16x32_bf16 v[40:43], v[158:161], v[196:199], v[40:43]
	v_mfma_f32_16x16x32_bf16 v[98:101], v[150:153], v[204:207], v[98:101]
	v_mfma_f32_16x16x32_bf16 v[32:35], v[158:161], v[204:207], v[32:35]
	v_mfma_f32_16x16x32_bf16 v[94:97], v[150:153], v[212:215], v[94:97]
	v_mfma_f32_16x16x32_bf16 v[48:51], v[158:161], v[212:215], v[48:51]
	s_setprio 0
	s_barrier
; #define PG8_STAGE(bufoff, gbase, voff) do { _Pragma("unroll") for (int _i = 0; _i < 2; ++_i) \
;         __builtin_amdgcn_global_load_lds((const unsigned*)((const char*)(gbase) + (voff)[_i]), (PG8_LAS unsigned*)(lds + (bufoff) + ldsw + _i * 8192), 16, 0, 0); } while (0)
; #define PG8_LDA(dst, b, h) do { _Pragma("unroll") for (int m = 0; m < 4; ++m) _Pragma("unroll") for (int k = 0; k < 2; ++k) dst[m][k] = *(const PG8_LAS bf16x8*)(lds + PG8_SA(b, h) + aoff + m * 2048 + k * 1024); } while (0)
; #define PG8_MMA(ai, bj, At, Bt) do { __builtin_amdgcn_s_setprio(1); _Pragma("unroll") for (int m = 0; m < 4; ++m) _Pragma("unroll") for (int n = 0; n < 2; ++n) _Pragma("unroll") for (int k = 0; k < 2; ++k) \
;         acc[ai][bj][m][n] = __builtin_amdgcn_mfma_f32_16x16x32_bf16(Bt[n][k], At[m][k], acc[ai][bj][m][n], 0, 0, 0); __builtin_amdgcn_s_setprio(0); } while (0)
; #define PG8_WAIT_V(n) asm volatile("s_waitcnt vmcnt(" #n ")" ::: "memory")
; #define PG8_WAIT_L(n) asm volatile("s_waitcnt lgkmcnt(" #n ")" ::: "memory")
; #define PG8_BAR __builtin_amdgcn_s_barrier()
; #define PG8_SCHED __builtin_amdgcn_sched_barrier(0)
; template <class Epi, class Sched, bool ALIGN_EPI = false, bool SP2 = false>
; __device__ __forceinline__ void gemm_phase(PG8_LAS unsigned char* lds, const Gemm g, const Sched& S, const Epi& E, int tid_in) {
;     ...
;             PG8_LDA(At, 1, 1); PG8_STAGE(PG8_SB(1, 0), b3, voffB); PG8_STAGE(PG8_SB(1, 1), b3 + hstep, voffB); PG8_STAGE(PG8_SA(1, 0), a3, voffA);
;             PG8_WAIT_V(8); PG8_WAIT_L(0); PG8_BAR; PG8_MMA(1, 0, At, B0); PG8_MMA(1, 1, At, B1); PG8_BAR; PG8_SCHED;
	s_add_i32 s30, s45, s9
	v_lshl_add_u64 v[172:173], v[172:173], 0, s[92:93]
	s_mov_b32 m0, s30
	ds_read_b128 v[162:165], v216 offset:49152
	ds_read_b128 v[166:169], v216 offset:50176
	ds_read_b128 v[192:195], v216 offset:51200
	ds_read_b128 v[196:199], v216 offset:52224
	ds_read_b128 v[200:203], v216 offset:53248
	ds_read_b128 v[204:207], v216 offset:54272
	ds_read_b128 v[208:211], v216 offset:55296
	ds_read_b128 v[212:215], v216 offset:56320
	global_load_lds_dwordx4 v[172:173], off
	s_add_i32 m0, s30, 0x2000
	s_add_u32 s28, s28, 0x40080
	v_lshl_add_u64 v[172:173], v[220:221], 0, s[92:93]
	s_addc_u32 s29, s29, 0
	s_add_i32 s30, s46, s9
	global_load_lds_dwordx4 v[172:173], off
	v_lshl_add_u64 v[172:173], s[28:29], 0, v[178:179]
	s_mov_b32 m0, s30
	s_nop 0
	global_load_lds_dwordx4 v[172:173], off
	v_lshl_add_u64 v[172:173], s[28:29], 0, v[182:183]
	s_add_i32 m0, s30, 0x2000
	s_nop 0
	global_load_lds_dwordx4 v[172:173], off
	v_lshl_add_u64 v[172:173], v[222:223], 0, s[92:93]
	s_mov_b32 m0, s85
	s_nop 0
	global_load_lds_dwordx4 v[172:173], off
	v_lshl_add_u64 v[172:173], v[224:225], 0, s[92:93]
	s_mov_b32 m0, s8
	s_nop 0
	global_load_lds_dwordx4 v[172:173], off
	s_waitcnt vmcnt(8)
	s_waitcnt lgkmcnt(0)
	s_barrier
	s_setprio 1
	s_waitcnt lgkmcnt(0)
	v_mfma_f32_16x16x32_bf16 v[82:85], v[122:125], v[162:165], v[82:85]
	v_mfma_f32_16x16x32_bf16 v[20:23], v[130:133], v[162:165], v[20:23]
	v_mfma_f32_16x16x32_bf16 v[70:73], v[122:125], v[192:195], v[70:73]
	v_mfma_f32_16x16x32_bf16 v[12:15], v[130:133], v[192:195], v[12:15]
	v_mfma_f32_16x16x32_bf16 v[60:63], v[122:125], v[200:203], v[60:63]
	v_mfma_f32_16x16x32_bf16 v[4:7], v[130:133], v[200:203], v[4:7]
	v_mfma_f32_16x16x32_bf16 v[90:93], v[122:125], v[208:211], v[90:93]
	v_mfma_f32_16x16x32_bf16 v[28:31], v[130:133], v[208:211], v[28:31]
	v_mfma_f32_16x16x32_bf16 v[82:85], v[126:129], v[166:169], v[82:85]
	v_mfma_f32_16x16x32_bf16 v[20:23], v[134:137], v[166:169], v[20:23]
	v_mfma_f32_16x16x32_bf16 v[70:73], v[126:129], v[196:199], v[70:73]
	v_mfma_f32_16x16x32_bf16 v[12:15], v[134:137], v[196:199], v[12:15]
	v_mfma_f32_16x16x32_bf16 v[60:63], v[126:129], v[204:207], v[60:63]
	v_mfma_f32_16x16x32_bf16 v[4:7], v[134:137], v[204:207], v[4:7]
	v_mfma_f32_16x16x32_bf16 v[90:93], v[126:129], v[212:215], v[90:93]
	v_mfma_f32_16x16x32_bf16 v[28:31], v[134:137], v[212:215], v[28:31]
	v_mfma_f32_16x16x32_bf16 v[74:77], v[146:149], v[162:165], v[74:77]
	v_mfma_f32_16x16x32_bf16 v[16:19], v[154:157], v[162:165], v[16:19]
	v_mfma_f32_16x16x32_bf16 v[66:69], v[146:149], v[192:195], v[66:69]
	v_mfma_f32_16x16x32_bf16 v[8:11], v[154:157], v[192:195], v[8:11]
	v_mfma_f32_16x16x32_bf16 v[56:59], v[146:149], v[200:203], v[56:59]
	v_mfma_f32_16x16x32_bf16 v[0:3], v[154:157], v[200:203], v[0:3]
	v_mfma_f32_16x16x32_bf16 v[86:89], v[146:149], v[208:211], v[86:89]
	v_mfma_f32_16x16x32_bf16 v[24:27], v[154:157], v[208:211], v[24:27]
	v_mfma_f32_16x16x32_bf16 v[74:77], v[150:153], v[166:169], v[74:77]
	v_mfma_f32_16x16x32_bf16 v[16:19], v[158:161], v[166:169], v[16:19]
	v_mfma_f32_16x16x32_bf16 v[66:69], v[150:153], v[196:199], v[66:69]
	v_mfma_f32_16x16x32_bf16 v[8:11], v[158:161], v[196:199], v[8:11]
	v_mfma_f32_16x16x32_bf16 v[56:59], v[150:153], v[204:207], v[56:59]
	v_mfma_f32_16x16x32_bf16 v[0:3], v[158:161], v[204:207], v[0:3]
	v_mfma_f32_16x16x32_bf16 v[86:89], v[150:153], v[212:215], v[86:89]
	v_mfma_f32_16x16x32_bf16 v[24:27], v[158:161], v[212:215], v[24:27]
	s_setprio 0
	s_barrier
	s_add_i32 s44, s44, 2
	s_add_u32 s26, s26, 0x100
	s_addc_u32 s27, s27, 0
	s_add_u32 s42, s42, 0x100
	s_addc_u32 s43, s43, 0
	s_cmp_gt_u32 s44, 13
	s_cbranch_scc0 .LBB0_242
	s_branch .Lpeel_exit_1

; #define PG8_BAR __builtin_amdgcn_s_barrier()
; template <class Epi, class Sched, bool ALIGN_EPI = false, bool SP2 = false>
; __device__ __forceinline__ void gemm_phase(PG8_LAS unsigned char* lds, const Gemm g, const Sched& S, const Epi& E, int tid_in) {
;     ...
;         if constexpr (ALIGN_EPI) { if (wr == 0) PG8_BAR; }
.Lpeel_exit_1:
	s_and_b64 vcc, exec, s[16:17]
	s_cbranch_vccz .LBB0_245
	s_barrier

; #define PG8_STAGE(bufoff, gbase, voff) do { _Pragma("unroll") for (int _i = 0; _i < 2; ++_i) \
;         __builtin_amdgcn_global_load_lds((const unsigned*)((const char*)(gbase) + (voff)[_i]), (PG8_LAS unsigned*)(lds + (bufoff) + ldsw + _i * 8192), 16, 0, 0); } while (0)
; #define PG8_LDA(dst, b, h) do { _Pragma("unroll") for (int m = 0; m < 4; ++m) _Pragma("unroll") for (int k = 0; k < 2; ++k) dst[m][k] = *(const PG8_LAS bf16x8*)(lds + PG8_SA(b, h) + aoff + m * 2048 + k * 1024); } while (0)
; #define PG8_LDB(dst, b, h) do { _Pragma("unroll") for (int n = 0; n < 2; ++n) _Pragma("unroll") for (int k = 0; k < 2; ++k) dst[n][k] = *(const PG8_LAS bf16x8*)(lds + PG8_SB(b, h) + boff + n * 2048 + k * 1024); } while (0)
; #define PG8_MMA(ai, bj, At, Bt) do { __builtin_amdgcn_s_setprio(1); _Pragma("unroll") for (int m = 0; m < 4; ++m) _Pragma("unroll") for (int n = 0; n < 2; ++n) _Pragma("unroll") for (int k = 0; k < 2; ++k) \
;         acc[ai][bj][m][n] = __builtin_amdgcn_mfma_f32_16x16x32_bf16(Bt[n][k], At[m][k], acc[ai][bj][m][n], 0, 0, 0); __builtin_amdgcn_s_setprio(0); } while (0)
; #define PG8_WAIT_V(n) asm volatile("s_waitcnt vmcnt(" #n ")" ::: "memory")
; #define PG8_WAIT_L(n) asm volatile("s_waitcnt lgkmcnt(" #n ")" ::: "memory")
; #define PG8_BAR __builtin_amdgcn_s_barrier()
; template <class Epi, class Sched, bool ALIGN_EPI = false, bool SP2 = false>
; __device__ __forceinline__ void gemm_phase(PG8_LAS unsigned char* lds, const Gemm g, const Sched& S, const Epi& E, int tid_in) {
;     ...
;             const bool last = (t == nt - 2);
;             const char* a1 = cA + (size_t)(t + 1) * kstep;
;             const char* a2 = last ? nA : cA + (size_t)(t + 2) * kstep; const char* b2 = last ? nB : cB + (size_t)(t + 2) * kstep;
;             const char* a3 = a2 + kstep; const char* b3 = b2 + kstep;
;             if (last && has_next) S.a_ready(nxt);
;             if constexpr (SP2) {
;             PG8_LDB(B0, 0, 0); PG8_LDB(B1, 0, 1); PG8_SCHED; PG8_LDA(At, 0, 0); PG8_STAGE(PG8_SA(1, 1), a1 + hstep, voffA);
;             PG8_WAIT_V(8); PG8_WAIT_L(0); PG8_BAR; PG8_MMA(0, 0, At, B0); PG8_MMA(0, 1, At, B1); PG8_BAR; PG8_SCHED;
;     DI void operator()(const pg8::f32x4 (&acc)[2][2][4][2], const pg8::Unit& u, int wr, int wc, int fr, int fq) const {
;     ...
;                 const int row = u.pm * 256 + ai * 128 + wr * 64 + m * 16 + fr; const float rs = rstdx[row];
.LBB0_753:
	s_ashr_i32 s19, s18, 31
	s_lshl_b64 s[20:21], s[18:19], 19
	s_add_u32 s20, s7, s20
	s_addc_u32 s21, s34, s21
	s_and_b64 s[22:23], s[38:39], exec
	s_cselect_b32 s19, s21, s27
	s_cselect_b32 s44, s20, s26
	s_ashr_i32 s17, s16, 31
	s_lshl_b64 s[22:23], s[16:17], 19
	v_readlane_b32 s30, v255, 3
	v_readlane_b32 s31, v255, 4
	s_add_u32 s22, s30, s22
	s_addc_u32 s23, s31, s23
	s_and_b64 s[30:31], s[38:39], exec
	s_cselect_b32 s17, s23, s29
	s_cselect_b32 s45, s22, s28
	s_add_u32 s26, s26, 0x40080
	s_addc_u32 s27, s27, 0
	s_add_u32 s46, s28, 0x100
	s_addc_u32 s47, s29, 0
	s_mov_b32 s48, -2
	s_waitcnt vmcnt(0)
	s_lshl_b32 s100, s24, 8
	v_add_u32_e32 v173, s100, v144
	v_mov_b32_e32 v250, v173
	v_ashrrev_i32_e32 v251, 31, v250
	v_lshl_add_u64 v[250:251], v[250:251], 2, s[8:9]
	global_load_dword v174, v[250:251], off
	v_add_u32_e32 v232, s100, v146
	v_ashrrev_i32_e32 v233, 31, v232
	v_lshl_add_u64 v[232:233], v[232:233], 2, s[8:9]
	global_load_dword v232, v[232:233], off
	v_add_u32_e32 v238, s100, v147
	v_ashrrev_i32_e32 v239, 31, v238
	v_lshl_add_u64 v[238:239], v[238:239], 2, s[8:9]
	global_load_dword v238, v[238:239], off
	v_add_u32_e32 v242, s100, v148
	v_ashrrev_i32_e32 v243, 31, v242
	v_lshl_add_u64 v[242:243], v[242:243], 2, s[8:9]
	global_load_dword v242, v[242:243], off
	v_add_u32_e32 v244, 0x80, v173
	v_ashrrev_i32_e32 v245, 31, v244
	v_lshl_add_u64 v[244:245], v[244:245], 2, s[8:9]
	global_load_dword v244, v[244:245], off
	v_add_u32_e32 v246, 0x90, v173
	v_ashrrev_i32_e32 v247, 31, v246
	v_lshl_add_u64 v[246:247], v[246:247], 2, s[8:9]
	global_load_dword v246, v[246:247], off
	v_add_u32_e32 v248, 0xa0, v173
	v_ashrrev_i32_e32 v249, 31, v248
	v_lshl_add_u64 v[248:249], v[248:249], 2, s[8:9]
	global_load_dword v248, v[248:249], off
	v_add_u32_e32 v250, 0xb0, v173
	v_ashrrev_i32_e32 v251, 31, v250
	v_lshl_add_u64 v[250:251], v[250:251], 2, s[8:9]
	global_load_dword v250, v[250:251], off
	s_add_u32 s28, s26, 0xfffc0080
	s_addc_u32 s29, s27, -1
	s_add_i32 s49, 0, 0x10000
	s_cmp_eq_u32 s48, 12
	s_cselect_b32 s31, s19, s29
	s_cselect_b32 s30, s44, s28
	v_add_u32_e32 v142, s49, v145
	s_cselect_b32 s29, s17, s47
	s_cselect_b32 s28, s45, s46
	s_add_i32 s52, 0, 0x14000
	ds_read_b128 v[150:153], v142
	ds_read_b128 v[154:157], v142 offset:1024
	ds_read_b128 v[158:161], v142 offset:2048
	ds_read_b128 v[162:165], v142 offset:3072
	v_add_u32_e32 v142, s52, v145
	ds_read_b128 v[166:169], v142
	ds_read_b128 v[176:179], v142 offset:1024
	ds_read_b128 v[180:183], v142 offset:2048
	ds_read_b128 v[184:187], v142 offset:3072
	v_lshl_add_u64 v[142:143], s[26:27], 0, v[138:139]
	s_add_i32 m0, s35, 0xc000
	ds_read_b128 v[188:191], v149
	ds_read_b128 v[192:195], v149 offset:1024
	ds_read_b128 v[196:199], v149 offset:2048
	ds_read_b128 v[200:203], v149 offset:3072
	ds_read_b128 v[204:207], v149 offset:4096
	ds_read_b128 v[208:211], v149 offset:5120
	ds_read_b128 v[212:215], v149 offset:6144
	ds_read_b128 v[216:219], v149 offset:7168
	global_load_lds_dwordx4 v[142:143], off
	v_lshl_add_u64 v[142:143], s[26:27], 0, v[140:141]
	s_add_i32 m0, s35, 0xe000
	s_nop 0
	global_load_lds_dwordx4 v[142:143], off
	s_waitcnt vmcnt(8)
	s_waitcnt lgkmcnt(0)
	s_barrier
	s_setprio 1
	s_waitcnt lgkmcnt(0)
	v_mfma_f32_16x16x32_bf16 v[126:129], v[150:153], v[188:191], 0
	v_mfma_f32_16x16x32_bf16 v[122:125], v[158:161], v[188:191], 0
	v_mfma_f32_16x16x32_bf16 v[110:113], v[150:153], v[196:199], 0
	v_mfma_f32_16x16x32_bf16 v[106:109], v[158:161], v[196:199], 0
	v_mfma_f32_16x16x32_bf16 v[94:97], v[150:153], v[204:207], 0
	v_mfma_f32_16x16x32_bf16 v[90:93], v[158:161], v[204:207], 0
	v_mfma_f32_16x16x32_bf16 v[78:81], v[150:153], v[212:215], 0
	v_mfma_f32_16x16x32_bf16 v[74:77], v[158:161], v[212:215], 0
	v_mfma_f32_16x16x32_bf16 v[126:129], v[154:157], v[192:195], v[126:129]
	v_mfma_f32_16x16x32_bf16 v[122:125], v[162:165], v[192:195], v[122:125]
	v_mfma_f32_16x16x32_bf16 v[110:113], v[154:157], v[200:203], v[110:113]
	v_mfma_f32_16x16x32_bf16 v[106:109], v[162:165], v[200:203], v[106:109]
	v_mfma_f32_16x16x32_bf16 v[94:97], v[154:157], v[208:211], v[94:97]
	v_mfma_f32_16x16x32_bf16 v[90:93], v[162:165], v[208:211], v[90:93]
	v_mfma_f32_16x16x32_bf16 v[78:81], v[154:157], v[216:219], v[78:81]
	v_mfma_f32_16x16x32_bf16 v[74:77], v[162:165], v[216:219], v[74:77]
	v_mfma_f32_16x16x32_bf16 v[118:121], v[166:169], v[188:191], 0
	v_mfma_f32_16x16x32_bf16 v[114:117], v[180:183], v[188:191], 0
	v_mfma_f32_16x16x32_bf16 v[102:105], v[166:169], v[196:199], 0
	v_mfma_f32_16x16x32_bf16 v[98:101], v[180:183], v[196:199], 0
	v_mfma_f32_16x16x32_bf16 v[86:89], v[166:169], v[204:207], 0
	v_mfma_f32_16x16x32_bf16 v[82:85], v[180:183], v[204:207], 0
	v_mfma_f32_16x16x32_bf16 v[70:73], v[166:169], v[212:215], 0
	v_mfma_f32_16x16x32_bf16 v[66:69], v[180:183], v[212:215], 0
	v_mfma_f32_16x16x32_bf16 v[118:121], v[176:179], v[192:195], v[118:121]
	v_mfma_f32_16x16x32_bf16 v[114:117], v[184:187], v[192:195], v[114:117]
	v_mfma_f32_16x16x32_bf16 v[102:105], v[176:179], v[200:203], v[102:105]
	v_mfma_f32_16x16x32_bf16 v[98:101], v[184:187], v[200:203], v[98:101]
	v_mfma_f32_16x16x32_bf16 v[86:89], v[176:179], v[208:211], v[86:89]
	v_mfma_f32_16x16x32_bf16 v[82:85], v[184:187], v[208:211], v[82:85]
	v_mfma_f32_16x16x32_bf16 v[70:73], v[176:179], v[216:219], v[70:73]
	v_mfma_f32_16x16x32_bf16 v[66:69], v[184:187], v[216:219], v[66:69]
	s_setprio 0
	s_barrier
; #define PG8_STAGE(bufoff, gbase, voff) do { _Pragma("unroll") for (int _i = 0; _i < 2; ++_i) \
;         __builtin_amdgcn_global_load_lds((const unsigned*)((const char*)(gbase) + (voff)[_i]), (PG8_LAS unsigned*)(lds + (bufoff) + ldsw + _i * 8192), 16, 0, 0); } while (0)
; #define PG8_LDA(dst, b, h) do { _Pragma("unroll") for (int m = 0; m < 4; ++m) _Pragma("unroll") for (int k = 0; k < 2; ++k) dst[m][k] = *(const PG8_LAS bf16x8*)(lds + PG8_SA(b, h) + aoff + m * 2048 + k * 1024); } while (0)
; #define PG8_LDB(dst, b, h) do { _Pragma("unroll") for (int n = 0; n < 2; ++n) _Pragma("unroll") for (int k = 0; k < 2; ++k) dst[n][k] = *(const PG8_LAS bf16x8*)(lds + PG8_SB(b, h) + boff + n * 2048 + k * 1024); } while (0)
; #define PG8_MMA(ai, bj, At, Bt) do { __builtin_amdgcn_s_setprio(1); _Pragma("unroll") for (int m = 0; m < 4; ++m) _Pragma("unroll") for (int n = 0; n < 2; ++n) _Pragma("unroll") for (int k = 0; k < 2; ++k) \
;         acc[ai][bj][m][n] = __builtin_amdgcn_mfma_f32_16x16x32_bf16(Bt[n][k], At[m][k], acc[ai][bj][m][n], 0, 0, 0); __builtin_amdgcn_s_setprio(0); } while (0)
; #define PG8_WAIT_V(n) asm volatile("s_waitcnt vmcnt(" #n ")" ::: "memory")
; #define PG8_WAIT_L(n) asm volatile("s_waitcnt lgkmcnt(" #n ")" ::: "memory")
; #define PG8_BAR __builtin_amdgcn_s_barrier()
; #define PG8_SCHED __builtin_amdgcn_sched_barrier(0)
; template <class Epi, class Sched, bool ALIGN_EPI = false, bool SP2 = false>
; __device__ __forceinline__ void gemm_phase(PG8_LAS unsigned char* lds, const Gemm g, const Sched& S, const Epi& E, int tid_in) {
;     ...
;             PG8_LDA(At, 0, 1); PG8_STAGE(PG8_SB(0, 0), b2, voffB); PG8_STAGE(PG8_SB(0, 1), b2 + hstep, voffB); PG8_STAGE(PG8_SA(0, 0), a2, voffA);
;             PG8_WAIT_V(8); PG8_WAIT_L(0); PG8_BAR; PG8_MMA(1, 0, At, B0); PG8_MMA(1, 1, At, B1); PG8_BAR; PG8_SCHED;
;             PG8_LDB(B0, 1, 0); PG8_LDB(B1, 1, 1); PG8_SCHED; PG8_LDA(At, 1, 0); PG8_STAGE(PG8_SA(0, 1), a2 + hstep, voffA);
	s_add_i32 s49, s49, s6
	v_lshl_add_u64 v[142:143], s[28:29], 0, v[132:133]
	s_mov_b32 m0, s49
	ds_read_b128 v[188:191], v149 offset:16384
	ds_read_b128 v[192:195], v149 offset:17408
	ds_read_b128 v[196:199], v149 offset:18432
	ds_read_b128 v[200:203], v149 offset:19456
	ds_read_b128 v[204:207], v149 offset:20480
	ds_read_b128 v[208:211], v149 offset:21504
	ds_read_b128 v[212:215], v149 offset:22528
	ds_read_b128 v[216:219], v149 offset:23552
	global_load_lds_dwordx4 v[142:143], off
	s_add_i32 m0, s49, 0x2000
	s_add_u32 s50, s28, 0x40000
	v_lshl_add_u64 v[170:171], s[28:29], 0, v[136:137]
	s_addc_u32 s51, s29, 0
	s_add_i32 s49, s52, s6
	global_load_lds_dwordx4 v[170:171], off
	v_lshl_add_u64 v[220:221], s[50:51], 0, v[132:133]
	s_mov_b32 m0, s49
	v_lshl_add_u64 v[222:223], s[30:31], 0, v[134:135]
	global_load_lds_dwordx4 v[220:221], off
	v_lshl_add_u64 v[220:221], s[50:51], 0, v[136:137]
	s_add_i32 m0, s49, 0x2000
	s_nop 0
	global_load_lds_dwordx4 v[220:221], off
	v_lshl_add_u64 v[220:221], s[30:31], 0, v[130:131]
	s_mov_b32 m0, s35
	s_nop 0
	global_load_lds_dwordx4 v[220:221], off
	s_mov_b32 m0, s36
	s_nop 0
	global_load_lds_dwordx4 v[222:223], off
	s_waitcnt vmcnt(8)
	s_waitcnt lgkmcnt(0)
	s_barrier
	s_setprio 1
	s_waitcnt lgkmcnt(0)
	v_mfma_f32_16x16x32_bf16 v[60:63], v[150:153], v[188:191], 0
	v_mfma_f32_16x16x32_bf16 v[56:59], v[158:161], v[188:191], 0
	v_mfma_f32_16x16x32_bf16 v[44:47], v[150:153], v[196:199], 0
	v_mfma_f32_16x16x32_bf16 v[40:43], v[158:161], v[196:199], 0
	v_mfma_f32_16x16x32_bf16 v[28:31], v[150:153], v[204:207], 0
	v_mfma_f32_16x16x32_bf16 v[24:27], v[158:161], v[204:207], 0
	v_mfma_f32_16x16x32_bf16 v[12:15], v[150:153], v[212:215], 0
	v_mfma_f32_16x16x32_bf16 v[8:11], v[158:161], v[212:215], 0
	v_mfma_f32_16x16x32_bf16 v[60:63], v[154:157], v[192:195], v[60:63]
	v_mfma_f32_16x16x32_bf16 v[56:59], v[162:165], v[192:195], v[56:59]
	v_mfma_f32_16x16x32_bf16 v[44:47], v[154:157], v[200:203], v[44:47]
	v_mfma_f32_16x16x32_bf16 v[40:43], v[162:165], v[200:203], v[40:43]
	v_mfma_f32_16x16x32_bf16 v[28:31], v[154:157], v[208:211], v[28:31]
	v_mfma_f32_16x16x32_bf16 v[24:27], v[162:165], v[208:211], v[24:27]
	v_mfma_f32_16x16x32_bf16 v[12:15], v[154:157], v[216:219], v[12:15]
	v_mfma_f32_16x16x32_bf16 v[8:11], v[162:165], v[216:219], v[8:11]
	v_mfma_f32_16x16x32_bf16 v[52:55], v[166:169], v[188:191], 0
	v_mfma_f32_16x16x32_bf16 v[48:51], v[180:183], v[188:191], 0
	v_mfma_f32_16x16x32_bf16 v[36:39], v[166:169], v[196:199], 0
	v_mfma_f32_16x16x32_bf16 v[32:35], v[180:183], v[196:199], 0
	v_mfma_f32_16x16x32_bf16 v[20:23], v[166:169], v[204:207], 0
	v_mfma_f32_16x16x32_bf16 v[16:19], v[180:183], v[204:207], 0
	v_mfma_f32_16x16x32_bf16 v[4:7], v[166:169], v[212:215], 0
	v_mfma_f32_16x16x32_bf16 v[0:3], v[180:183], v[212:215], 0
	v_mfma_f32_16x16x32_bf16 v[52:55], v[176:179], v[192:195], v[52:55]
	v_mfma_f32_16x16x32_bf16 v[48:51], v[184:187], v[192:195], v[48:51]
	v_mfma_f32_16x16x32_bf16 v[36:39], v[176:179], v[200:203], v[36:39]
	v_mfma_f32_16x16x32_bf16 v[32:35], v[184:187], v[200:203], v[32:35]
	v_mfma_f32_16x16x32_bf16 v[20:23], v[176:179], v[208:211], v[20:23]
	v_mfma_f32_16x16x32_bf16 v[16:19], v[184:187], v[208:211], v[16:19]
	v_mfma_f32_16x16x32_bf16 v[4:7], v[176:179], v[216:219], v[4:7]
	v_mfma_f32_16x16x32_bf16 v[0:3], v[184:187], v[216:219], v[0:3]
	s_setprio 0
	s_barrier
	s_add_i32 s49, 0, 0x18000
	s_add_i32 s50, 0, 0x1c000
	v_add_u32_e32 v162, s49, v145
	v_add_u32_e32 v172, s50, v145
	ds_read_b128 v[150:153], v162
	ds_read_b128 v[154:157], v162 offset:1024
	ds_read_b128 v[158:161], v162 offset:2048
	ds_read_b128 v[162:165], v162 offset:3072
	ds_read_b128 v[166:169], v172
	ds_read_b128 v[176:179], v172 offset:1024
	ds_read_b128 v[180:183], v172 offset:2048
	ds_read_b128 v[184:187], v172 offset:3072
	s_add_u32 s30, s30, 0x40000
	s_addc_u32 s31, s31, 0
	s_mov_b32 m0, s37
	v_lshl_add_u64 v[224:225], s[30:31], 0, v[130:131]
	ds_read_b128 v[188:191], v149 offset:32768
	ds_read_b128 v[192:195], v149 offset:33792
	ds_read_b128 v[196:199], v149 offset:34816
	ds_read_b128 v[200:203], v149 offset:35840
	ds_read_b128 v[204:207], v149 offset:36864
	ds_read_b128 v[208:211], v149 offset:37888
	ds_read_b128 v[212:215], v149 offset:38912
	ds_read_b128 v[216:219], v149 offset:39936
	global_load_lds_dwordx4 v[224:225], off
	v_lshl_add_u64 v[224:225], s[30:31], 0, v[134:135]
	s_mov_b32 m0, s40
	s_nop 0
	global_load_lds_dwordx4 v[224:225], off
	s_waitcnt vmcnt(8)
	s_waitcnt lgkmcnt(0)
	s_barrier
; #define PG8_STAGE(bufoff, gbase, voff) do { _Pragma("unroll") for (int _i = 0; _i < 2; ++_i) \
;         __builtin_amdgcn_global_load_lds((const unsigned*)((const char*)(gbase) + (voff)[_i]), (PG8_LAS unsigned*)(lds + (bufoff) + ldsw + _i * 8192), 16, 0, 0); } while (0)
; #define PG8_LDA(dst, b, h) do { _Pragma("unroll") for (int m = 0; m < 4; ++m) _Pragma("unroll") for (int k = 0; k < 2; ++k) dst[m][k] = *(const PG8_LAS bf16x8*)(lds + PG8_SA(b, h) + aoff + m * 2048 + k * 1024); } while (0)
; #define PG8_MMA(ai, bj, At, Bt) do { __builtin_amdgcn_s_setprio(1); _Pragma("unroll") for (int m = 0; m < 4; ++m) _Pragma("unroll") for (int n = 0; n < 2; ++n) _Pragma("unroll") for (int k = 0; k < 2; ++k) \
;         acc[ai][bj][m][n] = __builtin_amdgcn_mfma_f32_16x16x32_bf16(Bt[n][k], At[m][k], acc[ai][bj][m][n], 0, 0, 0); __builtin_amdgcn_s_setprio(0); } while (0)
; #define PG8_WAIT_V(n) asm volatile("s_waitcnt vmcnt(" #n ")" ::: "memory")
; #define PG8_WAIT_L(n) asm volatile("s_waitcnt lgkmcnt(" #n ")" ::: "memory")
; #define PG8_BAR __builtin_amdgcn_s_barrier()
; #define PG8_SCHED __builtin_amdgcn_sched_barrier(0)
; template <class Epi, class Sched, bool ALIGN_EPI = false, bool SP2 = false>
; __device__ __forceinline__ void gemm_phase(PG8_LAS unsigned char* lds, const Gemm g, const Sched& S, const Epi& E, int tid_in) {
;     ...
;         for (int t = tb_; t < te_; t += 2) {
;     ...
;             PG8_WAIT_V(8); PG8_WAIT_L(0); PG8_BAR; PG8_MMA(0, 0, At, B0); PG8_MMA(0, 1, At, B1); PG8_BAR; PG8_SCHED;
;             PG8_LDA(At, 1, 1); PG8_STAGE(PG8_SB(1, 0), b3, voffB); PG8_STAGE(PG8_SB(1, 1), b3 + hstep, voffB); PG8_STAGE(PG8_SA(1, 0), a3, voffA);
;             PG8_WAIT_V(8); PG8_WAIT_L(0); PG8_BAR; PG8_MMA(1, 0, At, B0); PG8_MMA(1, 1, At, B1); PG8_BAR; PG8_SCHED;
	s_setprio 1
	s_waitcnt lgkmcnt(0)
	v_mfma_f32_16x16x32_bf16 v[126:129], v[150:153], v[188:191], v[126:129]
	v_mfma_f32_16x16x32_bf16 v[122:125], v[158:161], v[188:191], v[122:125]
	v_mfma_f32_16x16x32_bf16 v[110:113], v[150:153], v[196:199], v[110:113]
	v_mfma_f32_16x16x32_bf16 v[106:109], v[158:161], v[196:199], v[106:109]
	v_mfma_f32_16x16x32_bf16 v[94:97], v[150:153], v[204:207], v[94:97]
	v_mfma_f32_16x16x32_bf16 v[90:93], v[158:161], v[204:207], v[90:93]
	v_mfma_f32_16x16x32_bf16 v[78:81], v[150:153], v[212:215], v[78:81]
	v_mfma_f32_16x16x32_bf16 v[74:77], v[158:161], v[212:215], v[74:77]
	v_mfma_f32_16x16x32_bf16 v[126:129], v[154:157], v[192:195], v[126:129]
	v_mfma_f32_16x16x32_bf16 v[122:125], v[162:165], v[192:195], v[122:125]
	v_mfma_f32_16x16x32_bf16 v[110:113], v[154:157], v[200:203], v[110:113]
	v_mfma_f32_16x16x32_bf16 v[106:109], v[162:165], v[200:203], v[106:109]
	v_mfma_f32_16x16x32_bf16 v[94:97], v[154:157], v[208:211], v[94:97]
	v_mfma_f32_16x16x32_bf16 v[90:93], v[162:165], v[208:211], v[90:93]
	v_mfma_f32_16x16x32_bf16 v[78:81], v[154:157], v[216:219], v[78:81]
	v_mfma_f32_16x16x32_bf16 v[74:77], v[162:165], v[216:219], v[74:77]
	v_mfma_f32_16x16x32_bf16 v[118:121], v[166:169], v[188:191], v[118:121]
	v_mfma_f32_16x16x32_bf16 v[114:117], v[180:183], v[188:191], v[114:117]
	v_mfma_f32_16x16x32_bf16 v[102:105], v[166:169], v[196:199], v[102:105]
	v_mfma_f32_16x16x32_bf16 v[98:101], v[180:183], v[196:199], v[98:101]
	v_mfma_f32_16x16x32_bf16 v[86:89], v[166:169], v[204:207], v[86:89]
	v_mfma_f32_16x16x32_bf16 v[82:85], v[180:183], v[204:207], v[82:85]
	v_mfma_f32_16x16x32_bf16 v[70:73], v[166:169], v[212:215], v[70:73]
	v_mfma_f32_16x16x32_bf16 v[66:69], v[180:183], v[212:215], v[66:69]
	v_mfma_f32_16x16x32_bf16 v[118:121], v[176:179], v[192:195], v[118:121]
	v_mfma_f32_16x16x32_bf16 v[114:117], v[184:187], v[192:195], v[114:117]
	v_mfma_f32_16x16x32_bf16 v[102:105], v[176:179], v[200:203], v[102:105]
	v_mfma_f32_16x16x32_bf16 v[98:101], v[184:187], v[200:203], v[98:101]
	v_mfma_f32_16x16x32_bf16 v[86:89], v[176:179], v[208:211], v[86:89]
	v_mfma_f32_16x16x32_bf16 v[82:85], v[184:187], v[208:211], v[82:85]
	v_mfma_f32_16x16x32_bf16 v[70:73], v[176:179], v[216:219], v[70:73]
	v_mfma_f32_16x16x32_bf16 v[66:69], v[184:187], v[216:219], v[66:69]
	s_setprio 0
	s_barrier
	s_add_i32 s30, s49, s6
	v_lshl_add_u64 v[142:143], v[142:143], 0, s[92:93]
	s_mov_b32 m0, s30
	ds_read_b128 v[188:191], v149 offset:49152
	ds_read_b128 v[192:195], v149 offset:50176
	ds_read_b128 v[196:199], v149 offset:51200
	ds_read_b128 v[200:203], v149 offset:52224
	ds_read_b128 v[204:207], v149 offset:53248
	ds_read_b128 v[208:211], v149 offset:54272
	ds_read_b128 v[212:215], v149 offset:55296
	ds_read_b128 v[216:219], v149 offset:56320
	global_load_lds_dwordx4 v[142:143], off
	s_add_i32 m0, s30, 0x2000
	s_add_u32 s28, s28, 0x40080
	v_lshl_add_u64 v[142:143], v[170:171], 0, s[92:93]
	s_addc_u32 s29, s29, 0
	s_add_i32 s30, s50, s6
	global_load_lds_dwordx4 v[142:143], off
	v_lshl_add_u64 v[142:143], s[28:29], 0, v[132:133]
	s_mov_b32 m0, s30
	s_nop 0
	global_load_lds_dwordx4 v[142:143], off
	v_lshl_add_u64 v[142:143], s[28:29], 0, v[136:137]
	s_add_i32 m0, s30, 0x2000
	s_nop 0
	global_load_lds_dwordx4 v[142:143], off
	v_lshl_add_u64 v[142:143], v[220:221], 0, s[92:93]
	s_mov_b32 m0, s41
	s_nop 0
	global_load_lds_dwordx4 v[142:143], off
	v_lshl_add_u64 v[142:143], v[222:223], 0, s[92:93]
	s_mov_b32 m0, s42
	s_nop 0
	global_load_lds_dwordx4 v[142:143], off
	s_waitcnt vmcnt(8)
	s_waitcnt lgkmcnt(0)
	s_barrier
	s_setprio 1
	s_waitcnt lgkmcnt(0)
	v_mfma_f32_16x16x32_bf16 v[60:63], v[150:153], v[188:191], v[60:63]
	v_mfma_f32_16x16x32_bf16 v[56:59], v[158:161], v[188:191], v[56:59]
	v_mfma_f32_16x16x32_bf16 v[44:47], v[150:153], v[196:199], v[44:47]
	v_mfma_f32_16x16x32_bf16 v[40:43], v[158:161], v[196:199], v[40:43]
	v_mfma_f32_16x16x32_bf16 v[28:31], v[150:153], v[204:207], v[28:31]
	v_mfma_f32_16x16x32_bf16 v[24:27], v[158:161], v[204:207], v[24:27]
	v_mfma_f32_16x16x32_bf16 v[12:15], v[150:153], v[212:215], v[12:15]
	v_mfma_f32_16x16x32_bf16 v[8:11], v[158:161], v[212:215], v[8:11]
	v_mfma_f32_16x16x32_bf16 v[60:63], v[154:157], v[192:195], v[60:63]
	v_mfma_f32_16x16x32_bf16 v[56:59], v[162:165], v[192:195], v[56:59]
	v_mfma_f32_16x16x32_bf16 v[44:47], v[154:157], v[200:203], v[44:47]
	v_mfma_f32_16x16x32_bf16 v[40:43], v[162:165], v[200:203], v[40:43]
	v_mfma_f32_16x16x32_bf16 v[28:31], v[154:157], v[208:211], v[28:31]
	v_mfma_f32_16x16x32_bf16 v[24:27], v[162:165], v[208:211], v[24:27]
	v_mfma_f32_16x16x32_bf16 v[12:15], v[154:157], v[216:219], v[12:15]
	v_mfma_f32_16x16x32_bf16 v[8:11], v[162:165], v[216:219], v[8:11]
	v_mfma_f32_16x16x32_bf16 v[52:55], v[166:169], v[188:191], v[52:55]
	v_mfma_f32_16x16x32_bf16 v[48:51], v[180:183], v[188:191], v[48:51]
	v_mfma_f32_16x16x32_bf16 v[36:39], v[166:169], v[196:199], v[36:39]
	v_mfma_f32_16x16x32_bf16 v[32:35], v[180:183], v[196:199], v[32:35]
	v_mfma_f32_16x16x32_bf16 v[20:23], v[166:169], v[204:207], v[20:23]
	v_mfma_f32_16x16x32_bf16 v[16:19], v[180:183], v[204:207], v[16:19]
	v_mfma_f32_16x16x32_bf16 v[4:7], v[166:169], v[212:215], v[4:7]
	v_mfma_f32_16x16x32_bf16 v[0:3], v[180:183], v[212:215], v[0:3]
	v_mfma_f32_16x16x32_bf16 v[52:55], v[176:179], v[192:195], v[52:55]
	v_mfma_f32_16x16x32_bf16 v[48:51], v[184:187], v[192:195], v[48:51]
	v_mfma_f32_16x16x32_bf16 v[36:39], v[176:179], v[200:203], v[36:39]
	v_mfma_f32_16x16x32_bf16 v[32:35], v[184:187], v[200:203], v[32:35]
	v_mfma_f32_16x16x32_bf16 v[20:23], v[176:179], v[208:211], v[20:23]
	v_mfma_f32_16x16x32_bf16 v[16:19], v[184:187], v[208:211], v[16:19]
	v_mfma_f32_16x16x32_bf16 v[4:7], v[176:179], v[216:219], v[4:7]
	v_mfma_f32_16x16x32_bf16 v[0:3], v[184:187], v[216:219], v[0:3]
	s_setprio 0
	s_barrier
	s_add_i32 s48, s48, 2
	s_add_u32 s26, s26, 0x100
	s_addc_u32 s27, s27, 0
	s_add_u32 s46, s46, 0x100
	s_addc_u32 s47, s47, 0
	s_cmp_gt_u32 s48, 13
	s_cbranch_scc0 .LBB0_754
	s_branch .Lpeel_exit_0
; #define PG8_STAGE(bufoff, gbase, voff) do { _Pragma("unroll") for (int _i = 0; _i < 2; ++_i) \
;         __builtin_amdgcn_global_load_lds((const unsigned*)((const char*)(gbase) + (voff)[_i]), (PG8_LAS unsigned*)(lds + (bufoff) + ldsw + _i * 8192), 16, 0, 0); } while (0)
; #define PG8_LDA(dst, b, h) do { _Pragma("unroll") for (int m = 0; m < 4; ++m) _Pragma("unroll") for (int k = 0; k < 2; ++k) dst[m][k] = *(const PG8_LAS bf16x8*)(lds + PG8_SA(b, h) + aoff + m * 2048 + k * 1024); } while (0)
; #define PG8_LDB(dst, b, h) do { _Pragma("unroll") for (int n = 0; n < 2; ++n) _Pragma("unroll") for (int k = 0; k < 2; ++k) dst[n][k] = *(const PG8_LAS bf16x8*)(lds + PG8_SB(b, h) + boff + n * 2048 + k * 1024); } while (0)
; #define PG8_MMA(ai, bj, At, Bt) do { __builtin_amdgcn_s_setprio(1); _Pragma("unroll") for (int m = 0; m < 4; ++m) _Pragma("unroll") for (int n = 0; n < 2; ++n) _Pragma("unroll") for (int k = 0; k < 2; ++k) \
;         acc[ai][bj][m][n] = __builtin_amdgcn_mfma_f32_16x16x32_bf16(Bt[n][k], At[m][k], acc[ai][bj][m][n], 0, 0, 0); __builtin_amdgcn_s_setprio(0); } while (0)
; #define PG8_WAIT_V(n) asm volatile("s_waitcnt vmcnt(" #n ")" ::: "memory")
; #define PG8_BAR __builtin_amdgcn_s_barrier()
; template <class Epi, class Sched, bool ALIGN_EPI = false, bool SP2 = false>
; __device__ __forceinline__ void gemm_phase(PG8_LAS unsigned char* lds, const Gemm g, const Sched& S, const Epi& E, int tid_in) {
;     ...
;         for (int t = tb_; t < te_; t += 2) {
;             const bool last = (t == nt - 2);
;             const char* a1 = cA + (size_t)(t + 1) * kstep;
;             const char* a2 = last ? nA : cA + (size_t)(t + 2) * kstep; const char* b2 = last ? nB : cB + (size_t)(t + 2) * kstep;
;             const char* a3 = a2 + kstep; const char* b3 = b2 + kstep;
;             if (last && has_next) S.a_ready(nxt);
;             if constexpr (SP2) {
;             PG8_LDB(B0, 0, 0); PG8_LDB(B1, 0, 1); PG8_SCHED; PG8_LDA(At, 0, 0); PG8_STAGE(PG8_SA(1, 1), a1 + hstep, voffA);
;             PG8_WAIT_V(8); PG8_WAIT_L(0); PG8_BAR; PG8_MMA(0, 0, At, B0); PG8_MMA(0, 1, At, B1); PG8_BAR; PG8_SCHED;
;             PG8_LDA(At, 0, 1); PG8_STAGE(PG8_SB(0, 0), b2, voffB); PG8_STAGE(PG8_SB(0, 1), b2 + hstep, voffB); PG8_STAGE(PG8_SA(0, 0), a2, voffA);
;             PG8_WAIT_V(8); PG8_WAIT_L(0); PG8_BAR; PG8_MMA(1, 0, At, B0); PG8_MMA(1, 1, At, B1); PG8_BAR; PG8_SCHED;
.LBB0_754:
	s_add_u32 s28, s26, 0xfffc0080
	s_addc_u32 s29, s27, -1
	s_add_i32 s49, 0, 0x10000
	s_cmp_eq_u32 s48, 12
	s_cselect_b32 s31, s19, s29
	s_cselect_b32 s30, s44, s28
	v_add_u32_e32 v142, s49, v145
	s_cselect_b32 s29, s17, s47
	s_cselect_b32 s28, s45, s46
	s_add_i32 s52, 0, 0x14000
	ds_read_b128 v[150:153], v142
	ds_read_b128 v[154:157], v142 offset:1024
	ds_read_b128 v[158:161], v142 offset:2048
	ds_read_b128 v[162:165], v142 offset:3072
	v_add_u32_e32 v142, s52, v145
	ds_read_b128 v[166:169], v142
	ds_read_b128 v[176:179], v142 offset:1024
	ds_read_b128 v[180:183], v142 offset:2048
	ds_read_b128 v[184:187], v142 offset:3072
	v_lshl_add_u64 v[142:143], s[26:27], 0, v[138:139]
	s_add_i32 m0, s35, 0xc000
	ds_read_b128 v[188:191], v149
	ds_read_b128 v[192:195], v149 offset:1024
	ds_read_b128 v[196:199], v149 offset:2048
	ds_read_b128 v[200:203], v149 offset:3072
	ds_read_b128 v[204:207], v149 offset:4096
	ds_read_b128 v[208:211], v149 offset:5120
	ds_read_b128 v[212:215], v149 offset:6144
	ds_read_b128 v[216:219], v149 offset:7168
	global_load_lds_dwordx4 v[142:143], off
	v_lshl_add_u64 v[142:143], s[26:27], 0, v[140:141]
	s_add_i32 m0, s35, 0xe000
	s_nop 0
	global_load_lds_dwordx4 v[142:143], off
	s_waitcnt vmcnt(8)
	s_waitcnt lgkmcnt(0)
	s_barrier
	s_setprio 1
	s_waitcnt lgkmcnt(0)
	v_mfma_f32_16x16x32_bf16 v[126:129], v[150:153], v[188:191], v[126:129]
	v_mfma_f32_16x16x32_bf16 v[122:125], v[158:161], v[188:191], v[122:125]
	v_mfma_f32_16x16x32_bf16 v[110:113], v[150:153], v[196:199], v[110:113]
	v_mfma_f32_16x16x32_bf16 v[106:109], v[158:161], v[196:199], v[106:109]
	v_mfma_f32_16x16x32_bf16 v[94:97], v[150:153], v[204:207], v[94:97]
	v_mfma_f32_16x16x32_bf16 v[90:93], v[158:161], v[204:207], v[90:93]
	v_mfma_f32_16x16x32_bf16 v[78:81], v[150:153], v[212:215], v[78:81]
	v_mfma_f32_16x16x32_bf16 v[74:77], v[158:161], v[212:215], v[74:77]
	v_mfma_f32_16x16x32_bf16 v[126:129], v[154:157], v[192:195], v[126:129]
	v_mfma_f32_16x16x32_bf16 v[122:125], v[162:165], v[192:195], v[122:125]
	v_mfma_f32_16x16x32_bf16 v[110:113], v[154:157], v[200:203], v[110:113]
	v_mfma_f32_16x16x32_bf16 v[106:109], v[162:165], v[200:203], v[106:109]
	v_mfma_f32_16x16x32_bf16 v[94:97], v[154:157], v[208:211], v[94:97]
	v_mfma_f32_16x16x32_bf16 v[90:93], v[162:165], v[208:211], v[90:93]
	v_mfma_f32_16x16x32_bf16 v[78:81], v[154:157], v[216:219], v[78:81]
	v_mfma_f32_16x16x32_bf16 v[74:77], v[162:165], v[216:219], v[74:77]
	v_mfma_f32_16x16x32_bf16 v[118:121], v[166:169], v[188:191], v[118:121]
	v_mfma_f32_16x16x32_bf16 v[114:117], v[180:183], v[188:191], v[114:117]
	v_mfma_f32_16x16x32_bf16 v[102:105], v[166:169], v[196:199], v[102:105]
	v_mfma_f32_16x16x32_bf16 v[98:101], v[180:183], v[196:199], v[98:101]
	v_mfma_f32_16x16x32_bf16 v[86:89], v[166:169], v[204:207], v[86:89]
	v_mfma_f32_16x16x32_bf16 v[82:85], v[180:183], v[204:207], v[82:85]
	v_mfma_f32_16x16x32_bf16 v[70:73], v[166:169], v[212:215], v[70:73]
	v_mfma_f32_16x16x32_bf16 v[66:69], v[180:183], v[212:215], v[66:69]
	v_mfma_f32_16x16x32_bf16 v[118:121], v[176:179], v[192:195], v[118:121]
	v_mfma_f32_16x16x32_bf16 v[114:117], v[184:187], v[192:195], v[114:117]
	v_mfma_f32_16x16x32_bf16 v[102:105], v[176:179], v[200:203], v[102:105]
	v_mfma_f32_16x16x32_bf16 v[98:101], v[184:187], v[200:203], v[98:101]
	v_mfma_f32_16x16x32_bf16 v[86:89], v[176:179], v[208:211], v[86:89]
	v_mfma_f32_16x16x32_bf16 v[82:85], v[184:187], v[208:211], v[82:85]
	v_mfma_f32_16x16x32_bf16 v[70:73], v[176:179], v[216:219], v[70:73]
	v_mfma_f32_16x16x32_bf16 v[66:69], v[184:187], v[216:219], v[66:69]
	s_setprio 0
	s_barrier
	s_add_i32 s49, s49, s6
	v_lshl_add_u64 v[142:143], s[28:29], 0, v[132:133]
	s_mov_b32 m0, s49
	ds_read_b128 v[188:191], v149 offset:16384
	ds_read_b128 v[192:195], v149 offset:17408
	ds_read_b128 v[196:199], v149 offset:18432
	ds_read_b128 v[200:203], v149 offset:19456
	ds_read_b128 v[204:207], v149 offset:20480
	ds_read_b128 v[208:211], v149 offset:21504
	ds_read_b128 v[212:215], v149 offset:22528
	ds_read_b128 v[216:219], v149 offset:23552
	global_load_lds_dwordx4 v[142:143], off
	s_add_i32 m0, s49, 0x2000
	s_add_u32 s50, s28, 0x40000
	v_lshl_add_u64 v[170:171], s[28:29], 0, v[136:137]
	s_addc_u32 s51, s29, 0
	s_add_i32 s49, s52, s6
	global_load_lds_dwordx4 v[170:171], off
	v_lshl_add_u64 v[220:221], s[50:51], 0, v[132:133]
	s_mov_b32 m0, s49
	v_lshl_add_u64 v[222:223], s[30:31], 0, v[134:135]
	global_load_lds_dwordx4 v[220:221], off
	v_lshl_add_u64 v[220:221], s[50:51], 0, v[136:137]
	s_add_i32 m0, s49, 0x2000
	s_nop 0
	global_load_lds_dwordx4 v[220:221], off
	v_lshl_add_u64 v[220:221], s[30:31], 0, v[130:131]
	s_mov_b32 m0, s35
	s_nop 0
	global_load_lds_dwordx4 v[220:221], off
	s_mov_b32 m0, s36
	s_nop 0
	global_load_lds_dwordx4 v[222:223], off
	s_waitcnt vmcnt(8)
	s_waitcnt lgkmcnt(0)
	s_barrier
; #define PG8_STAGE(bufoff, gbase, voff) do { _Pragma("unroll") for (int _i = 0; _i < 2; ++_i) \
;         __builtin_amdgcn_global_load_lds((const unsigned*)((const char*)(gbase) + (voff)[_i]), (PG8_LAS unsigned*)(lds + (bufoff) + ldsw + _i * 8192), 16, 0, 0); } while (0)
; #define PG8_LDA(dst, b, h) do { _Pragma("unroll") for (int m = 0; m < 4; ++m) _Pragma("unroll") for (int k = 0; k < 2; ++k) dst[m][k] = *(const PG8_LAS bf16x8*)(lds + PG8_SA(b, h) + aoff + m * 2048 + k * 1024); } while (0)
; #define PG8_LDB(dst, b, h) do { _Pragma("unroll") for (int n = 0; n < 2; ++n) _Pragma("unroll") for (int k = 0; k < 2; ++k) dst[n][k] = *(const PG8_LAS bf16x8*)(lds + PG8_SB(b, h) + boff + n * 2048 + k * 1024); } while (0)
; #define PG8_MMA(ai, bj, At, Bt) do { __builtin_amdgcn_s_setprio(1); _Pragma("unroll") for (int m = 0; m < 4; ++m) _Pragma("unroll") for (int n = 0; n < 2; ++n) _Pragma("unroll") for (int k = 0; k < 2; ++k) \
;         acc[ai][bj][m][n] = __builtin_amdgcn_mfma_f32_16x16x32_bf16(Bt[n][k], At[m][k], acc[ai][bj][m][n], 0, 0, 0); __builtin_amdgcn_s_setprio(0); } while (0)
; #define PG8_WAIT_V(n) asm volatile("s_waitcnt vmcnt(" #n ")" ::: "memory")
; #define PG8_WAIT_L(n) asm volatile("s_waitcnt lgkmcnt(" #n ")" ::: "memory")
; #define PG8_BAR __builtin_amdgcn_s_barrier()
; #define PG8_SCHED __builtin_amdgcn_sched_barrier(0)
; template <class Epi, class Sched, bool ALIGN_EPI = false, bool SP2 = false>
; __device__ __forceinline__ void gemm_phase(PG8_LAS unsigned char* lds, const Gemm g, const Sched& S, const Epi& E, int tid_in) {
;     ...
;             PG8_WAIT_V(8); PG8_WAIT_L(0); PG8_BAR; PG8_MMA(1, 0, At, B0); PG8_MMA(1, 1, At, B1); PG8_BAR; PG8_SCHED;
;             PG8_LDB(B0, 1, 0); PG8_LDB(B1, 1, 1); PG8_SCHED; PG8_LDA(At, 1, 0); PG8_STAGE(PG8_SA(0, 1), a2 + hstep, voffA);
;             PG8_WAIT_V(8); PG8_WAIT_L(0); PG8_BAR; PG8_MMA(0, 0, At, B0); PG8_MMA(0, 1, At, B1); PG8_BAR; PG8_SCHED;
	s_setprio 1
	s_waitcnt lgkmcnt(0)
	v_mfma_f32_16x16x32_bf16 v[60:63], v[150:153], v[188:191], v[60:63]
	v_mfma_f32_16x16x32_bf16 v[56:59], v[158:161], v[188:191], v[56:59]
	v_mfma_f32_16x16x32_bf16 v[44:47], v[150:153], v[196:199], v[44:47]
	v_mfma_f32_16x16x32_bf16 v[40:43], v[158:161], v[196:199], v[40:43]
	v_mfma_f32_16x16x32_bf16 v[28:31], v[150:153], v[204:207], v[28:31]
	v_mfma_f32_16x16x32_bf16 v[24:27], v[158:161], v[204:207], v[24:27]
	v_mfma_f32_16x16x32_bf16 v[12:15], v[150:153], v[212:215], v[12:15]
	v_mfma_f32_16x16x32_bf16 v[8:11], v[158:161], v[212:215], v[8:11]
	v_mfma_f32_16x16x32_bf16 v[60:63], v[154:157], v[192:195], v[60:63]
	v_mfma_f32_16x16x32_bf16 v[56:59], v[162:165], v[192:195], v[56:59]
	v_mfma_f32_16x16x32_bf16 v[44:47], v[154:157], v[200:203], v[44:47]
	v_mfma_f32_16x16x32_bf16 v[40:43], v[162:165], v[200:203], v[40:43]
	v_mfma_f32_16x16x32_bf16 v[28:31], v[154:157], v[208:211], v[28:31]
	v_mfma_f32_16x16x32_bf16 v[24:27], v[162:165], v[208:211], v[24:27]
	v_mfma_f32_16x16x32_bf16 v[12:15], v[154:157], v[216:219], v[12:15]
	v_mfma_f32_16x16x32_bf16 v[8:11], v[162:165], v[216:219], v[8:11]
	v_mfma_f32_16x16x32_bf16 v[52:55], v[166:169], v[188:191], v[52:55]
	v_mfma_f32_16x16x32_bf16 v[48:51], v[180:183], v[188:191], v[48:51]
	v_mfma_f32_16x16x32_bf16 v[36:39], v[166:169], v[196:199], v[36:39]
	v_mfma_f32_16x16x32_bf16 v[32:35], v[180:183], v[196:199], v[32:35]
	v_mfma_f32_16x16x32_bf16 v[20:23], v[166:169], v[204:207], v[20:23]
	v_mfma_f32_16x16x32_bf16 v[16:19], v[180:183], v[204:207], v[16:19]
	v_mfma_f32_16x16x32_bf16 v[4:7], v[166:169], v[212:215], v[4:7]
	v_mfma_f32_16x16x32_bf16 v[0:3], v[180:183], v[212:215], v[0:3]
	v_mfma_f32_16x16x32_bf16 v[52:55], v[176:179], v[192:195], v[52:55]
	v_mfma_f32_16x16x32_bf16 v[48:51], v[184:187], v[192:195], v[48:51]
	v_mfma_f32_16x16x32_bf16 v[36:39], v[176:179], v[200:203], v[36:39]
	v_mfma_f32_16x16x32_bf16 v[32:35], v[184:187], v[200:203], v[32:35]
	v_mfma_f32_16x16x32_bf16 v[20:23], v[176:179], v[208:211], v[20:23]
	v_mfma_f32_16x16x32_bf16 v[16:19], v[184:187], v[208:211], v[16:19]
	v_mfma_f32_16x16x32_bf16 v[4:7], v[176:179], v[216:219], v[4:7]
	v_mfma_f32_16x16x32_bf16 v[0:3], v[184:187], v[216:219], v[0:3]
	s_setprio 0
	s_barrier
	s_add_i32 s49, 0, 0x18000
	s_add_i32 s50, 0, 0x1c000
	v_add_u32_e32 v162, s49, v145
	v_add_u32_e32 v172, s50, v145
	ds_read_b128 v[150:153], v162
	ds_read_b128 v[154:157], v162 offset:1024
	ds_read_b128 v[158:161], v162 offset:2048
	ds_read_b128 v[162:165], v162 offset:3072
	ds_read_b128 v[166:169], v172
	ds_read_b128 v[176:179], v172 offset:1024
	ds_read_b128 v[180:183], v172 offset:2048
	ds_read_b128 v[184:187], v172 offset:3072
	s_add_u32 s30, s30, 0x40000
	s_addc_u32 s31, s31, 0
	s_mov_b32 m0, s37
	v_lshl_add_u64 v[224:225], s[30:31], 0, v[130:131]
	ds_read_b128 v[188:191], v149 offset:32768
	ds_read_b128 v[192:195], v149 offset:33792
	ds_read_b128 v[196:199], v149 offset:34816
	ds_read_b128 v[200:203], v149 offset:35840
	ds_read_b128 v[204:207], v149 offset:36864
	ds_read_b128 v[208:211], v149 offset:37888
	ds_read_b128 v[212:215], v149 offset:38912
	ds_read_b128 v[216:219], v149 offset:39936
	global_load_lds_dwordx4 v[224:225], off
	v_lshl_add_u64 v[224:225], s[30:31], 0, v[134:135]
	s_mov_b32 m0, s40
	s_nop 0
	global_load_lds_dwordx4 v[224:225], off
	s_waitcnt vmcnt(8)
	s_waitcnt lgkmcnt(0)
	s_barrier
	s_setprio 1
	s_waitcnt lgkmcnt(0)
	v_mfma_f32_16x16x32_bf16 v[126:129], v[150:153], v[188:191], v[126:129]
	v_mfma_f32_16x16x32_bf16 v[122:125], v[158:161], v[188:191], v[122:125]
	v_mfma_f32_16x16x32_bf16 v[110:113], v[150:153], v[196:199], v[110:113]
	v_mfma_f32_16x16x32_bf16 v[106:109], v[158:161], v[196:199], v[106:109]
	v_mfma_f32_16x16x32_bf16 v[94:97], v[150:153], v[204:207], v[94:97]
	v_mfma_f32_16x16x32_bf16 v[90:93], v[158:161], v[204:207], v[90:93]
	v_mfma_f32_16x16x32_bf16 v[78:81], v[150:153], v[212:215], v[78:81]
	v_mfma_f32_16x16x32_bf16 v[74:77], v[158:161], v[212:215], v[74:77]
	v_mfma_f32_16x16x32_bf16 v[126:129], v[154:157], v[192:195], v[126:129]
	v_mfma_f32_16x16x32_bf16 v[122:125], v[162:165], v[192:195], v[122:125]
	v_mfma_f32_16x16x32_bf16 v[110:113], v[154:157], v[200:203], v[110:113]
	v_mfma_f32_16x16x32_bf16 v[106:109], v[162:165], v[200:203], v[106:109]
	v_mfma_f32_16x16x32_bf16 v[94:97], v[154:157], v[208:211], v[94:97]
	v_mfma_f32_16x16x32_bf16 v[90:93], v[162:165], v[208:211], v[90:93]
	v_mfma_f32_16x16x32_bf16 v[78:81], v[154:157], v[216:219], v[78:81]
	v_mfma_f32_16x16x32_bf16 v[74:77], v[162:165], v[216:219], v[74:77]
	v_mfma_f32_16x16x32_bf16 v[118:121], v[166:169], v[188:191], v[118:121]
	v_mfma_f32_16x16x32_bf16 v[114:117], v[180:183], v[188:191], v[114:117]
	v_mfma_f32_16x16x32_bf16 v[102:105], v[166:169], v[196:199], v[102:105]
	v_mfma_f32_16x16x32_bf16 v[98:101], v[180:183], v[196:199], v[98:101]
	v_mfma_f32_16x16x32_bf16 v[86:89], v[166:169], v[204:207], v[86:89]
	v_mfma_f32_16x16x32_bf16 v[82:85], v[180:183], v[204:207], v[82:85]
	v_mfma_f32_16x16x32_bf16 v[70:73], v[166:169], v[212:215], v[70:73]
	v_mfma_f32_16x16x32_bf16 v[66:69], v[180:183], v[212:215], v[66:69]
	v_mfma_f32_16x16x32_bf16 v[118:121], v[176:179], v[192:195], v[118:121]
	v_mfma_f32_16x16x32_bf16 v[114:117], v[184:187], v[192:195], v[114:117]
	v_mfma_f32_16x16x32_bf16 v[102:105], v[176:179], v[200:203], v[102:105]
	v_mfma_f32_16x16x32_bf16 v[98:101], v[184:187], v[200:203], v[98:101]
	v_mfma_f32_16x16x32_bf16 v[86:89], v[176:179], v[208:211], v[86:89]
	v_mfma_f32_16x16x32_bf16 v[82:85], v[184:187], v[208:211], v[82:85]
	v_mfma_f32_16x16x32_bf16 v[70:73], v[176:179], v[216:219], v[70:73]
	v_mfma_f32_16x16x32_bf16 v[66:69], v[184:187], v[216:219], v[66:69]
	s_setprio 0
	s_barrier
; #define PG8_STAGE(bufoff, gbase, voff) do { _Pragma("unroll") for (int _i = 0; _i < 2; ++_i) \
;         __builtin_amdgcn_global_load_lds((const unsigned*)((const char*)(gbase) + (voff)[_i]), (PG8_LAS unsigned*)(lds + (bufoff) + ldsw + _i * 8192), 16, 0, 0); } while (0)
; #define PG8_LDA(dst, b, h) do { _Pragma("unroll") for (int m = 0; m < 4; ++m) _Pragma("unroll") for (int k = 0; k < 2; ++k) dst[m][k] = *(const PG8_LAS bf16x8*)(lds + PG8_SA(b, h) + aoff + m * 2048 + k * 1024); } while (0)
; #define PG8_MMA(ai, bj, At, Bt) do { __builtin_amdgcn_s_setprio(1); _Pragma("unroll") for (int m = 0; m < 4; ++m) _Pragma("unroll") for (int n = 0; n < 2; ++n) _Pragma("unroll") for (int k = 0; k < 2; ++k) \
;         acc[ai][bj][m][n] = __builtin_amdgcn_mfma_f32_16x16x32_bf16(Bt[n][k], At[m][k], acc[ai][bj][m][n], 0, 0, 0); __builtin_amdgcn_s_setprio(0); } while (0)
; #define PG8_WAIT_V(n) asm volatile("s_waitcnt vmcnt(" #n ")" ::: "memory")
; #define PG8_BAR __builtin_amdgcn_s_barrier()
; template <class Epi, class Sched, bool ALIGN_EPI = false, bool SP2 = false>
; __device__ __forceinline__ void gemm_phase(PG8_LAS unsigned char* lds, const Gemm g, const Sched& S, const Epi& E, int tid_in) {
;     ...
;             PG8_LDA(At, 1, 1); PG8_STAGE(PG8_SB(1, 0), b3, voffB); PG8_STAGE(PG8_SB(1, 1), b3 + hstep, voffB); PG8_STAGE(PG8_SA(1, 0), a3, voffA);
;             PG8_WAIT_V(8); PG8_WAIT_L(0); PG8_BAR; PG8_MMA(1, 0, At, B0); PG8_MMA(1, 1, At, B1); PG8_BAR; PG8_SCHED;
;     ...
;         if constexpr (ALIGN_EPI) { if (wr == 0) PG8_BAR; }
;         if constexpr (!Epi::AFTER_DRAIN) { E(acc, cur, wr, wc, fr, fq); S.done(cur); }
;     DI void operator()(const pg8::f32x4 (&acc)[2][2][4][2], const pg8::Unit& u, int wr, int wc, int fr, int fq) const {
; #pragma unroll
;         for (int ai = 0; ai < 2; ++ai)
; #pragma unroll
;             for (int m = 0; m < 4; ++m) {
;                 const int row = u.pm * 256 + ai * 128 + wr * 64 + m * 16 + fr; const float rs = rstdx[row];
; #pragma unroll
;                 for (int bj = 0; bj < 2; ++bj) {
;                     const pg8::f32x4 v0 = acc[ai][bj][m][0] * rs, v1 = acc[ai][bj][m][1] * rs;
;                     v4u w; w.x = pk2(v0[0], v0[1]); w.y = pk2(v0[2], v0[3]); w.z = pk2(v1[0], v1[1]); w.w = pk2(v1[2], v1[3]);
;                     *(v4u*)(O + (size_t)row * NPROJ + u.pn * 256 + bj * 128 + wc * 32 + 8 * fq) = w;
	s_add_i32 s30, s49, s6
	v_lshl_add_u64 v[142:143], v[142:143], 0, s[92:93]
	s_mov_b32 m0, s30
	ds_read_b128 v[188:191], v149 offset:49152
	ds_read_b128 v[192:195], v149 offset:50176
	ds_read_b128 v[196:199], v149 offset:51200
	ds_read_b128 v[200:203], v149 offset:52224
	ds_read_b128 v[204:207], v149 offset:53248
	ds_read_b128 v[208:211], v149 offset:54272
	ds_read_b128 v[212:215], v149 offset:55296
	ds_read_b128 v[216:219], v149 offset:56320
	global_load_lds_dwordx4 v[142:143], off
	s_add_i32 m0, s30, 0x2000
	s_add_u32 s28, s28, 0x40080
	v_lshl_add_u64 v[142:143], v[170:171], 0, s[92:93]
	s_addc_u32 s29, s29, 0
	s_add_i32 s30, s50, s6
	global_load_lds_dwordx4 v[142:143], off
	v_lshl_add_u64 v[142:143], s[28:29], 0, v[132:133]
	s_mov_b32 m0, s30
	s_nop 0
	global_load_lds_dwordx4 v[142:143], off
	v_lshl_add_u64 v[142:143], s[28:29], 0, v[136:137]
	s_add_i32 m0, s30, 0x2000
	s_nop 0
	global_load_lds_dwordx4 v[142:143], off
	v_lshl_add_u64 v[142:143], v[220:221], 0, s[92:93]
	s_mov_b32 m0, s41
	s_nop 0
	global_load_lds_dwordx4 v[142:143], off
	v_lshl_add_u64 v[142:143], v[222:223], 0, s[92:93]
	s_mov_b32 m0, s42
	s_nop 0
	global_load_lds_dwordx4 v[142:143], off
	s_waitcnt vmcnt(8)
	s_waitcnt lgkmcnt(0)
	s_barrier
	s_setprio 1
	s_waitcnt lgkmcnt(0)
	v_mfma_f32_16x16x32_bf16 v[60:63], v[150:153], v[188:191], v[60:63]
	v_mfma_f32_16x16x32_bf16 v[56:59], v[158:161], v[188:191], v[56:59]
	v_mfma_f32_16x16x32_bf16 v[44:47], v[150:153], v[196:199], v[44:47]
	v_mfma_f32_16x16x32_bf16 v[40:43], v[158:161], v[196:199], v[40:43]
	v_mfma_f32_16x16x32_bf16 v[28:31], v[150:153], v[204:207], v[28:31]
	v_mfma_f32_16x16x32_bf16 v[24:27], v[158:161], v[204:207], v[24:27]
	v_mfma_f32_16x16x32_bf16 v[12:15], v[150:153], v[212:215], v[12:15]
	v_mfma_f32_16x16x32_bf16 v[8:11], v[158:161], v[212:215], v[8:11]
	v_mfma_f32_16x16x32_bf16 v[60:63], v[154:157], v[192:195], v[60:63]
	v_mfma_f32_16x16x32_bf16 v[56:59], v[162:165], v[192:195], v[56:59]
	v_mfma_f32_16x16x32_bf16 v[44:47], v[154:157], v[200:203], v[44:47]
	v_mfma_f32_16x16x32_bf16 v[40:43], v[162:165], v[200:203], v[40:43]
	v_mfma_f32_16x16x32_bf16 v[28:31], v[154:157], v[208:211], v[28:31]
	v_mfma_f32_16x16x32_bf16 v[24:27], v[162:165], v[208:211], v[24:27]
	v_mfma_f32_16x16x32_bf16 v[12:15], v[154:157], v[216:219], v[12:15]
	v_mfma_f32_16x16x32_bf16 v[8:11], v[162:165], v[216:219], v[8:11]
	v_mfma_f32_16x16x32_bf16 v[52:55], v[166:169], v[188:191], v[52:55]
	v_mfma_f32_16x16x32_bf16 v[48:51], v[180:183], v[188:191], v[48:51]
	v_mfma_f32_16x16x32_bf16 v[36:39], v[166:169], v[196:199], v[36:39]
	v_mfma_f32_16x16x32_bf16 v[32:35], v[180:183], v[196:199], v[32:35]
	v_mfma_f32_16x16x32_bf16 v[20:23], v[166:169], v[204:207], v[20:23]
	v_mfma_f32_16x16x32_bf16 v[16:19], v[180:183], v[204:207], v[16:19]
	v_mfma_f32_16x16x32_bf16 v[4:7], v[166:169], v[212:215], v[4:7]
	v_mfma_f32_16x16x32_bf16 v[0:3], v[180:183], v[212:215], v[0:3]
	v_mfma_f32_16x16x32_bf16 v[52:55], v[176:179], v[192:195], v[52:55]
	v_mfma_f32_16x16x32_bf16 v[48:51], v[184:187], v[192:195], v[48:51]
	v_mfma_f32_16x16x32_bf16 v[36:39], v[176:179], v[200:203], v[36:39]
	v_mfma_f32_16x16x32_bf16 v[32:35], v[184:187], v[200:203], v[32:35]
	v_mfma_f32_16x16x32_bf16 v[20:23], v[176:179], v[208:211], v[20:23]
	v_mfma_f32_16x16x32_bf16 v[16:19], v[184:187], v[208:211], v[16:19]
	v_mfma_f32_16x16x32_bf16 v[4:7], v[176:179], v[216:219], v[4:7]
	v_mfma_f32_16x16x32_bf16 v[0:3], v[184:187], v[216:219], v[0:3]
	s_setprio 0
	s_barrier
	s_add_i32 s48, s48, 2
	s_add_u32 s26, s26, 0x100
	s_addc_u32 s27, s27, 0
	s_add_u32 s46, s46, 0x100
	s_addc_u32 s47, s47, 0
	s_cmp_gt_u32 s48, 13
	s_cbranch_scc0 .LBB0_754
.Lpeel_exit_0:
	s_and_b64 vcc, exec, s[14:15]
	s_cbranch_vccz .LBB0_757
	s_barrier
.LBB0_757:
	s_lshl_b32 s17, s24, 8
	v_add_u32_e32 v142, s17, v144
	v_ashrrev_i32_e32 v143, 31, v142
	s_lshl_b32 s24, s25, 8
	v_lshlrev_b64 v[152:153], 12, v[142:143]
	s_ashr_i32 s25, s24, 31
	s_lshl_b64 s[24:25], s[24:25], 1
	s_andn2_b64 vcc, exec, s[38:39]
	s_mov_b32 s46, 0xdb629599
	s_mov_b32 s47, 0xf534ddc0
	s_mov_b32 s52, 0xfc2757d1
	v_pk_mul_f32 v[126:127], v[126:127], v[174:175] op_sel_hi:[1,0]
	v_pk_mul_f32 v[154:155], v[124:125], v[174:175] op_sel_hi:[1,0]
	v_pk_mul_f32 v[124:125], v[122:123], v[174:175] op_sel_hi:[1,0]
	v_cvt_pk_bf16_f32 v122, v126, v127
	v_lshl_add_u64 v[126:127], s[12:13], 0, v[152:153]
	v_lshl_add_u64 v[126:127], v[126:127], 0, s[24:25]
	v_pk_mul_f32 v[128:129], v[128:129], v[174:175] op_sel_hi:[1,0]
	v_lshl_add_u64 v[126:127], v[126:127], 0, s[72:73]
	v_cvt_pk_bf16_f32 v123, v128, v129
	v_cvt_pk_bf16_f32 v124, v124, v125
	v_cvt_pk_bf16_f32 v125, v154, v155
	v_lshl_add_u64 v[126:127], v[126:127], 0, v[64:65]
	global_store_dwordx4 v[126:127], v[122:125], off
	v_pk_mul_f32 v[120:121], v[120:121], v[174:175] op_sel_hi:[1,0]
	v_pk_mul_f32 v[118:119], v[118:119], v[174:175] op_sel_hi:[1,0]
	v_pk_mul_f32 v[122:123], v[116:117], v[174:175] op_sel_hi:[1,0]
	v_pk_mul_f32 v[116:117], v[114:115], v[174:175] op_sel_hi:[1,0]
	v_cvt_pk_bf16_f32 v114, v118, v119
	v_cvt_pk_bf16_f32 v115, v120, v121
	v_cvt_pk_bf16_f32 v116, v116, v117
	v_cvt_pk_bf16_f32 v117, v122, v123
	global_store_dwordx4 v[126:127], v[114:117], off offset:256
	s_nop 1
	v_add_u32_e32 v114, s17, v146
	v_ashrrev_i32_e32 v115, 31, v114
	v_lshlrev_b64 v[114:115], 12, v[114:115]
	v_pk_mul_f32 v[110:111], v[110:111], v[232:233] op_sel_hi:[1,0]
	v_pk_mul_f32 v[118:119], v[108:109], v[232:233] op_sel_hi:[1,0]
	v_pk_mul_f32 v[108:109], v[106:107], v[232:233] op_sel_hi:[1,0]
	v_cvt_pk_bf16_f32 v106, v110, v111
	v_lshl_add_u64 v[110:111], s[12:13], 0, v[114:115]
	v_lshl_add_u64 v[110:111], v[110:111], 0, s[24:25]
; DI unsigned pk2(float lo, float hi) { f32x2_t v = {lo, hi}; bf16x2_t b = __builtin_convertvector(v, bf16x2_t); return __builtin_bit_cast(unsigned, b); }
;     DI void operator()(const pg8::f32x4 (&acc)[2][2][4][2], const pg8::Unit& u, int wr, int wc, int fr, int fq) const {
; #pragma unroll
;         for (int ai = 0; ai < 2; ++ai)
; #pragma unroll
;             for (int m = 0; m < 4; ++m) {
;                 const int row = u.pm * 256 + ai * 128 + wr * 64 + m * 16 + fr; const float rs = rstdx[row];
; #pragma unroll
;                 for (int bj = 0; bj < 2; ++bj) {
;                     const pg8::f32x4 v0 = acc[ai][bj][m][0] * rs, v1 = acc[ai][bj][m][1] * rs;
;                     v4u w; w.x = pk2(v0[0], v0[1]); w.y = pk2(v0[2], v0[3]); w.z = pk2(v1[0], v1[1]); w.w = pk2(v1[2], v1[3]);
;                     *(v4u*)(O + (size_t)row * NPROJ + u.pn * 256 + bj * 128 + wc * 32 + 8 * fq) = w;
	v_pk_mul_f32 v[112:113], v[112:113], v[232:233] op_sel_hi:[1,0]
	v_lshl_add_u64 v[110:111], v[110:111], 0, s[72:73]
	v_cvt_pk_bf16_f32 v107, v112, v113
	v_cvt_pk_bf16_f32 v108, v108, v109
	v_cvt_pk_bf16_f32 v109, v118, v119
	v_lshl_add_u64 v[110:111], v[110:111], 0, v[64:65]
	global_store_dwordx4 v[110:111], v[106:109], off
	v_pk_mul_f32 v[104:105], v[104:105], v[232:233] op_sel_hi:[1,0]
	v_pk_mul_f32 v[102:103], v[102:103], v[232:233] op_sel_hi:[1,0]
	v_pk_mul_f32 v[106:107], v[100:101], v[232:233] op_sel_hi:[1,0]
	v_pk_mul_f32 v[100:101], v[98:99], v[232:233] op_sel_hi:[1,0]
	v_cvt_pk_bf16_f32 v98, v102, v103
	v_cvt_pk_bf16_f32 v99, v104, v105
	v_cvt_pk_bf16_f32 v100, v100, v101
	v_cvt_pk_bf16_f32 v101, v106, v107
	global_store_dwordx4 v[110:111], v[98:101], off offset:256
	s_nop 1
	v_add_u32_e32 v98, s17, v147
	v_ashrrev_i32_e32 v99, 31, v98
	v_lshlrev_b64 v[98:99], 12, v[98:99]
	v_pk_mul_f32 v[94:95], v[94:95], v[238:239] op_sel_hi:[1,0]
	v_pk_mul_f32 v[102:103], v[92:93], v[238:239] op_sel_hi:[1,0]
	v_pk_mul_f32 v[92:93], v[90:91], v[238:239] op_sel_hi:[1,0]
	v_cvt_pk_bf16_f32 v90, v94, v95
	v_lshl_add_u64 v[94:95], s[12:13], 0, v[98:99]
	v_lshl_add_u64 v[94:95], v[94:95], 0, s[24:25]
	v_pk_mul_f32 v[96:97], v[96:97], v[238:239] op_sel_hi:[1,0]
	v_lshl_add_u64 v[94:95], v[94:95], 0, s[72:73]
	v_cvt_pk_bf16_f32 v91, v96, v97
	v_cvt_pk_bf16_f32 v92, v92, v93
	v_cvt_pk_bf16_f32 v93, v102, v103
	v_lshl_add_u64 v[94:95], v[94:95], 0, v[64:65]
	global_store_dwordx4 v[94:95], v[90:93], off
	v_pk_mul_f32 v[88:89], v[88:89], v[238:239] op_sel_hi:[1,0]
	v_pk_mul_f32 v[86:87], v[86:87], v[238:239] op_sel_hi:[1,0]
	v_pk_mul_f32 v[90:91], v[84:85], v[238:239] op_sel_hi:[1,0]
	v_pk_mul_f32 v[84:85], v[82:83], v[238:239] op_sel_hi:[1,0]
	v_cvt_pk_bf16_f32 v82, v86, v87
	v_cvt_pk_bf16_f32 v83, v88, v89
	v_cvt_pk_bf16_f32 v84, v84, v85
	v_cvt_pk_bf16_f32 v85, v90, v91
	global_store_dwordx4 v[94:95], v[82:85], off offset:256
	s_nop 1
	v_add_u32_e32 v82, s17, v148
	v_ashrrev_i32_e32 v83, 31, v82
	v_lshlrev_b64 v[82:83], 12, v[82:83]
	v_pk_mul_f32 v[78:79], v[78:79], v[242:243] op_sel_hi:[1,0]
	v_pk_mul_f32 v[86:87], v[76:77], v[242:243] op_sel_hi:[1,0]
	v_pk_mul_f32 v[76:77], v[74:75], v[242:243] op_sel_hi:[1,0]
	v_cvt_pk_bf16_f32 v74, v78, v79
	v_lshl_add_u64 v[78:79], s[12:13], 0, v[82:83]
	v_lshl_add_u64 v[78:79], v[78:79], 0, s[24:25]
	v_pk_mul_f32 v[80:81], v[80:81], v[242:243] op_sel_hi:[1,0]
	v_lshl_add_u64 v[78:79], v[78:79], 0, s[72:73]
	v_cvt_pk_bf16_f32 v75, v80, v81
	v_cvt_pk_bf16_f32 v76, v76, v77
	v_cvt_pk_bf16_f32 v77, v86, v87
	v_lshl_add_u64 v[78:79], v[78:79], 0, v[64:65]
	global_store_dwordx4 v[78:79], v[74:77], off
	v_pk_mul_f32 v[72:73], v[72:73], v[242:243] op_sel_hi:[1,0]
	v_pk_mul_f32 v[70:71], v[70:71], v[242:243] op_sel_hi:[1,0]
	v_pk_mul_f32 v[74:75], v[68:69], v[242:243] op_sel_hi:[1,0]
	v_pk_mul_f32 v[68:69], v[66:67], v[242:243] op_sel_hi:[1,0]
	v_cvt_pk_bf16_f32 v66, v70, v71
	v_cvt_pk_bf16_f32 v67, v72, v73
	v_cvt_pk_bf16_f32 v68, v68, v69
	v_cvt_pk_bf16_f32 v69, v74, v75
	global_store_dwordx4 v[78:79], v[66:69], off offset:256
	s_nop 1
	v_add_u32_e32 v66, 0x80, v142
	v_ashrrev_i32_e32 v67, 31, v66
	v_lshlrev_b64 v[66:67], 12, v[66:67]
	v_pk_mul_f32 v[60:61], v[60:61], v[244:245] op_sel_hi:[1,0]
	v_pk_mul_f32 v[70:71], v[58:59], v[244:245] op_sel_hi:[1,0]
	v_pk_mul_f32 v[58:59], v[56:57], v[244:245] op_sel_hi:[1,0]
	v_cvt_pk_bf16_f32 v56, v60, v61
	v_lshl_add_u64 v[60:61], s[12:13], 0, v[66:67]
	v_lshl_add_u64 v[60:61], v[60:61], 0, s[24:25]
	v_pk_mul_f32 v[62:63], v[62:63], v[244:245] op_sel_hi:[1,0]
	v_lshl_add_u64 v[60:61], v[60:61], 0, s[72:73]
	v_cvt_pk_bf16_f32 v57, v62, v63
	v_cvt_pk_bf16_f32 v58, v58, v59
	v_cvt_pk_bf16_f32 v59, v70, v71
	v_lshl_add_u64 v[60:61], v[60:61], 0, v[64:65]
	global_store_dwordx4 v[60:61], v[56:59], off
	v_pk_mul_f32 v[54:55], v[54:55], v[244:245] op_sel_hi:[1,0]
	v_pk_mul_f32 v[52:53], v[52:53], v[244:245] op_sel_hi:[1,0]
; #define PG8_BAR __builtin_amdgcn_s_barrier()
; DI unsigned pk2(float lo, float hi) { f32x2_t v = {lo, hi}; bf16x2_t b = __builtin_convertvector(v, bf16x2_t); return __builtin_bit_cast(unsigned, b); }
; template <class Epi, class Sched, bool ALIGN_EPI = false, bool SP2 = false>
; __device__ __forceinline__ void gemm_phase(PG8_LAS unsigned char* lds, const Gemm g, const Sched& S, const Epi& E, int tid_in) {
;     ...
;         if (!has_next) break;
; #pragma unroll
;         for (int a = 0; a < 2; ++a)
; #pragma unroll
;             for (int b = 0; b < 2; ++b)
; #pragma unroll
;                 for (int m = 0; m < 4; ++m)
; #pragma unroll
;                     for (int n = 0; n < 2; ++n) acc[a][b][m][n] = (f32x4){0.f, 0.f, 0.f, 0.f};
;         cur = nxt; cA = nA; cB = nB; ++ui;
;         if constexpr (ALIGN_EPI) { if (wr == 1) PG8_BAR; }
;     DI void operator()(const pg8::f32x4 (&acc)[2][2][4][2], const pg8::Unit& u, int wr, int wc, int fr, int fq) const {
; #pragma unroll
;         for (int ai = 0; ai < 2; ++ai)
; #pragma unroll
;             for (int m = 0; m < 4; ++m) {
;                 const int row = u.pm * 256 + ai * 128 + wr * 64 + m * 16 + fr; const float rs = rstdx[row];
; #pragma unroll
;                 for (int bj = 0; bj < 2; ++bj) {
;                     const pg8::f32x4 v0 = acc[ai][bj][m][0] * rs, v1 = acc[ai][bj][m][1] * rs;
;                     v4u w; w.x = pk2(v0[0], v0[1]); w.y = pk2(v0[2], v0[3]); w.z = pk2(v1[0], v1[1]); w.w = pk2(v1[2], v1[3]);
;                     *(v4u*)(O + (size_t)row * NPROJ + u.pn * 256 + bj * 128 + wc * 32 + 8 * fq) = w;
	v_pk_mul_f32 v[56:57], v[50:51], v[244:245] op_sel_hi:[1,0]
	v_pk_mul_f32 v[50:51], v[48:49], v[244:245] op_sel_hi:[1,0]
	v_cvt_pk_bf16_f32 v48, v52, v53
	v_cvt_pk_bf16_f32 v49, v54, v55
	v_cvt_pk_bf16_f32 v50, v50, v51
	v_cvt_pk_bf16_f32 v51, v56, v57
	global_store_dwordx4 v[60:61], v[48:51], off offset:256
	s_nop 1
	v_add_u32_e32 v48, 0x90, v142
	v_ashrrev_i32_e32 v49, 31, v48
	v_lshlrev_b64 v[48:49], 12, v[48:49]
	v_pk_mul_f32 v[44:45], v[44:45], v[246:247] op_sel_hi:[1,0]
	v_pk_mul_f32 v[52:53], v[42:43], v[246:247] op_sel_hi:[1,0]
	v_pk_mul_f32 v[42:43], v[40:41], v[246:247] op_sel_hi:[1,0]
	v_cvt_pk_bf16_f32 v40, v44, v45
	v_lshl_add_u64 v[44:45], s[12:13], 0, v[48:49]
	v_lshl_add_u64 v[44:45], v[44:45], 0, s[24:25]
	v_pk_mul_f32 v[46:47], v[46:47], v[246:247] op_sel_hi:[1,0]
	v_lshl_add_u64 v[44:45], v[44:45], 0, s[72:73]
	v_cvt_pk_bf16_f32 v41, v46, v47
	v_cvt_pk_bf16_f32 v42, v42, v43
	v_cvt_pk_bf16_f32 v43, v52, v53
	v_lshl_add_u64 v[44:45], v[44:45], 0, v[64:65]
	global_store_dwordx4 v[44:45], v[40:43], off
	v_pk_mul_f32 v[38:39], v[38:39], v[246:247] op_sel_hi:[1,0]
	v_pk_mul_f32 v[36:37], v[36:37], v[246:247] op_sel_hi:[1,0]
	v_pk_mul_f32 v[40:41], v[34:35], v[246:247] op_sel_hi:[1,0]
	v_pk_mul_f32 v[34:35], v[32:33], v[246:247] op_sel_hi:[1,0]
	v_cvt_pk_bf16_f32 v32, v36, v37
	v_cvt_pk_bf16_f32 v33, v38, v39
	v_cvt_pk_bf16_f32 v34, v34, v35
	v_cvt_pk_bf16_f32 v35, v40, v41
	global_store_dwordx4 v[44:45], v[32:35], off offset:256
	s_nop 1
	v_add_u32_e32 v32, 0xa0, v142
	v_ashrrev_i32_e32 v33, 31, v32
	v_lshlrev_b64 v[32:33], 12, v[32:33]
	v_pk_mul_f32 v[28:29], v[28:29], v[248:249] op_sel_hi:[1,0]
	v_pk_mul_f32 v[36:37], v[26:27], v[248:249] op_sel_hi:[1,0]
	v_pk_mul_f32 v[26:27], v[24:25], v[248:249] op_sel_hi:[1,0]
	v_cvt_pk_bf16_f32 v24, v28, v29
	v_lshl_add_u64 v[28:29], s[12:13], 0, v[32:33]
	v_lshl_add_u64 v[28:29], v[28:29], 0, s[24:25]
	v_pk_mul_f32 v[30:31], v[30:31], v[248:249] op_sel_hi:[1,0]
	v_lshl_add_u64 v[28:29], v[28:29], 0, s[72:73]
	v_cvt_pk_bf16_f32 v25, v30, v31
	v_cvt_pk_bf16_f32 v26, v26, v27
	v_cvt_pk_bf16_f32 v27, v36, v37
	v_lshl_add_u64 v[28:29], v[28:29], 0, v[64:65]
	global_store_dwordx4 v[28:29], v[24:27], off
	v_pk_mul_f32 v[22:23], v[22:23], v[248:249] op_sel_hi:[1,0]
	v_pk_mul_f32 v[20:21], v[20:21], v[248:249] op_sel_hi:[1,0]
	v_pk_mul_f32 v[24:25], v[18:19], v[248:249] op_sel_hi:[1,0]
	v_pk_mul_f32 v[18:19], v[16:17], v[248:249] op_sel_hi:[1,0]
	v_cvt_pk_bf16_f32 v16, v20, v21
	v_cvt_pk_bf16_f32 v17, v22, v23
	v_cvt_pk_bf16_f32 v18, v18, v19
	v_cvt_pk_bf16_f32 v19, v24, v25
	global_store_dwordx4 v[28:29], v[16:19], off offset:256
	s_nop 1
	v_add_u32_e32 v16, 0xb0, v142
	v_ashrrev_i32_e32 v17, 31, v16
	v_lshlrev_b64 v[16:17], 12, v[16:17]
	v_pk_mul_f32 v[12:13], v[12:13], v[250:251] op_sel_hi:[1,0]
	v_pk_mul_f32 v[20:21], v[10:11], v[250:251] op_sel_hi:[1,0]
	v_pk_mul_f32 v[10:11], v[8:9], v[250:251] op_sel_hi:[1,0]
	v_cvt_pk_bf16_f32 v8, v12, v13
	v_lshl_add_u64 v[12:13], s[12:13], 0, v[16:17]
	v_lshl_add_u64 v[12:13], v[12:13], 0, s[24:25]
	v_pk_mul_f32 v[14:15], v[14:15], v[250:251] op_sel_hi:[1,0]
	v_lshl_add_u64 v[12:13], v[12:13], 0, s[72:73]
	v_cvt_pk_bf16_f32 v9, v14, v15
	v_cvt_pk_bf16_f32 v10, v10, v11
	v_cvt_pk_bf16_f32 v11, v20, v21
	v_lshl_add_u64 v[12:13], v[12:13], 0, v[64:65]
	global_store_dwordx4 v[12:13], v[8:11], off
	v_pk_mul_f32 v[6:7], v[6:7], v[250:251] op_sel_hi:[1,0]
	v_pk_mul_f32 v[4:5], v[4:5], v[250:251] op_sel_hi:[1,0]
	v_pk_mul_f32 v[8:9], v[2:3], v[250:251] op_sel_hi:[1,0]
	v_pk_mul_f32 v[2:3], v[0:1], v[250:251] op_sel_hi:[1,0]
	v_cvt_pk_bf16_f32 v0, v4, v5
	v_cvt_pk_bf16_f32 v1, v6, v7
	v_cvt_pk_bf16_f32 v2, v2, v3
	v_cvt_pk_bf16_f32 v3, v8, v9
	s_mov_b64 s[24:25], -1
	global_store_dwordx4 v[12:13], v[0:3], off offset:256
	s_cbranch_vccnz .LBB0_746
	s_andn2_b64 vcc, exec, s[10:11]
	s_cbranch_vccnz .LBB0_745
	s_barrier
	s_branch .LBB0_745

; __device__ __forceinline__ void xcd_local_barrier(unsigned* ctr, unsigned epoch, int xtid) {
;     ...
;     if (xtid == 0) {
;         __builtin_amdgcn_s_waitcnt(0);
;         const unsigned target = (epoch + 1u) * 32u;
;         (void)__hip_atomic_fetch_add(ctr, 1u, __ATOMIC_RELAXED, __HIP_MEMORY_SCOPE_AGENT);
;         unsigned sp = 0u;
;         while (__hip_atomic_load(ctr, __ATOMIC_RELAXED, __HIP_MEMORY_SCOPE_AGENT) < target) { __builtin_amdgcn_s_sleep(1); if (++sp > (1u << 22)) break; }
.LBB0_956:
	s_or_b64 exec, exec, s[8:9]
	buffer_inv sc1
	s_lshl_b32 s8, s21, 5
	s_add_i32 s8, s8, 32
	s_mov_b32 s9, 0x400001
	s_branch .LBB0_958

; __device__ __forceinline__ void xcd_local_barrier(unsigned* ctr, unsigned epoch, int xtid) {
;     ...
;         while (__hip_atomic_load(ctr, __ATOMIC_RELAXED, __HIP_MEMORY_SCOPE_AGENT) < target) { __builtin_amdgcn_s_sleep(1); if (++sp > (1u << 22)) break; }
;         __builtin_amdgcn_fence(__ATOMIC_ACQUIRE, "agent");
;         asm volatile("s_waitcnt vmcnt(0)" ::: "memory");
.LBB0_958:
	global_load_dword v0, v65, s[54:55] sc1
	s_mov_b64 s[6:7], -1
	s_waitcnt vmcnt(0)
	v_cmp_le_u32_e32 vcc, s8, v0
	s_cbranch_vccnz .LBB0_957
	s_sleep 1
	global_load_dword v0, v65, s[54:55] sc1
	s_waitcnt vmcnt(0)
	v_cmp_gt_u32_e32 vcc, s8, v0
	s_cbranch_vccz .LBB0_957
	s_sleep 1
	global_load_dword v0, v65, s[54:55] sc1
	s_waitcnt vmcnt(0)
	v_cmp_gt_u32_e32 vcc, s8, v0
	s_cbranch_vccz .LBB0_957
	s_sleep 1
	global_load_dword v0, v65, s[54:55] sc1
	s_waitcnt vmcnt(0)
	v_cmp_gt_u32_e32 vcc, s8, v0
	s_cbranch_vccz .LBB0_957
	s_sleep 1
	global_load_dword v0, v65, s[54:55] sc1
	s_waitcnt vmcnt(0)
	v_cmp_gt_u32_e32 vcc, s8, v0
	s_cbranch_vccz .LBB0_957
	s_add_i32 s9, s9, -5
	s_cmp_eq_u32 s9, 0
	s_cselect_b64 s[6:7], -1, 0
	s_sleep 1
	s_branch .LBB0_957
.LBB0_964:
	s_waitcnt vmcnt(0)
.LBB0_965:
	s_or_b64 exec, exec, s[4:5]
	s_mov_b64 s[4:5], -1
	v_writelane_b32 v254, s4, 39
	s_add_i32 s8, s21, 1
	s_nop 0
	v_writelane_b32 v254, s5, 40
	s_barrier
